# out-proj epilogue: 16 residual loads issued up-front with counted vmcnt instead of a 32-step load/vmcnt(0)/store ladder; hyena neighbour prefetch via d16_hi without drains
# speedup vs baseline: 1.0030x; 1.0030x over previous
.LBB0_762:
	s_or_b64 exec, exec, s[6:7]
	v_add_u32_e32 v8, 8, v96
	v_and_b32_e32 v8, 56, v8
	v_cmp_ne_u32_e64 s[10:11], 0, v8
	s_and_saveexec_b64 s[6:7], s[10:11]
	s_cbranch_execz .LBB0_764
	global_load_short_d16_hi v37, v[18:19], off offset:16

.LBB0_766:
	s_or_b64 exec, exec, s[6:7]
	s_and_saveexec_b64 s[6:7], s[10:11]
	s_cbranch_execz .LBB0_768
	global_load_short_d16_hi v131, v[12:13], off offset:16

.LBB0_770:
	s_or_b64 exec, exec, s[6:7]
	s_and_saveexec_b64 s[6:7], s[10:11]
	s_cbranch_execz .LBB0_772
	v_add_co_u32_e32 v18, vcc, 0x4000, v18
	s_nop 1
	v_addc_co_u32_e32 v19, vcc, 0, v19, vcc
	global_load_short_d16_hi v50, v[18:19], off offset:16

.LBB0_774:
	s_or_b64 exec, exec, s[6:7]
	s_and_saveexec_b64 s[6:7], s[10:11]
	s_cbranch_execz .LBB0_776
	global_load_short_d16_hi v133, v[20:21], off offset:16

.LBB0_778:
	s_or_b64 exec, exec, s[6:7]
	s_and_saveexec_b64 s[6:7], s[10:11]
	s_cbranch_execz .LBB0_780
	global_load_short_d16_hi v39, v[34:35], off offset:16

.LBB0_782:
	s_or_b64 exec, exec, s[6:7]
	s_and_saveexec_b64 s[6:7], s[10:11]
	s_cbranch_execz .LBB0_784
	global_load_short_d16_hi v41, v[28:29], off offset:16

.LBB0_786:
	s_or_b64 exec, exec, s[6:7]
	s_and_saveexec_b64 s[6:7], s[10:11]
	s_cbranch_execz .LBB0_788
	v_add_co_u32_e32 v34, vcc, 0x4000, v34
	s_nop 1
	v_addc_co_u32_e32 v35, vcc, 0, v35, vcc
	global_load_short_d16_hi v54, v[34:35], off offset:16

.LBB0_790:
	s_or_b64 exec, exec, s[6:7]
	s_and_saveexec_b64 s[6:7], s[10:11]
	s_cbranch_execz .LBB0_792
	global_load_short_d16_hi v43, v[44:45], off offset:16

.LBB0_793:
	s_waitcnt vmcnt(0)
	v_or_b32_e32 v189, v232, v224
	v_or_b32_e32 v190, v231, v223
	v_or_b32_e32 v191, v230, v222
	v_or_b32_e32 v192, v229, v221
	v_or_b32_e32 v193, v228, v220
	v_or_b32_e32 v194, v227, v219
	v_or_b32_e32 v195, v226, v218
	v_or_b32_e32 v196, v233, v225
	s_waitcnt lgkmcnt(0)
	ds_read_b64 v[40:41], v122
	v_add_u32_e32 v44, v167, v168
	v_add_u32_e32 v46, v165, v168
	ds_read_b64 v[42:43], v121
	ds_read_b64 v[44:45], v44
	ds_read_b64 v[46:47], v46
	s_cmp_eq_u32 s15, s54
	s_waitcnt lgkmcnt(3)
	v_lshlrev_b32_e32 v48, 16, v40
	s_waitcnt lgkmcnt(2)
	v_lshlrev_b32_e32 v50, 16, v42
	v_and_b32_e32 v51, 0xffff0000, v42
	v_lshlrev_b32_e32 v42, 16, v43
	v_and_b32_e32 v43, 0xffff0000, v43
	v_and_b32_e32 v49, 0xffff0000, v40
	v_pk_fma_f32 v[50:51], v[120:121], v[50:51], v[100:101] op_sel_hi:[0,1,1]
	v_lshlrev_b32_e32 v40, 16, v41
	v_and_b32_e32 v41, 0xffff0000, v41
	v_pk_fma_f32 v[42:43], v[120:121], v[42:43], v[102:103] op_sel_hi:[0,1,1]
	v_pk_mul_f32 v[48:49], v[50:51], v[48:49]
	v_pk_mul_f32 v[40:41], v[42:43], v[40:41]
	v_cvt_pk_bf16_f32 v42, v48, v49
	v_cvt_pk_bf16_f32 v43, v40, v41
	v_lshl_add_u64 v[40:41], v[140:141], 0, s[30:31]
	s_waitcnt lgkmcnt(0)
	v_lshlrev_b32_e32 v48, 16, v46
	v_and_b32_e32 v49, 0xffff0000, v46
	v_lshlrev_b32_e32 v46, 16, v47
	v_and_b32_e32 v47, 0xffff0000, v47
	global_store_dwordx2 v[40:41], v[42:43], off
	v_lshlrev_b32_e32 v42, 16, v44
	v_and_b32_e32 v43, 0xffff0000, v44
	v_pk_fma_f32 v[48:49], v[120:121], v[48:49], v[96:97] op_sel_hi:[0,1,1]
	v_lshlrev_b32_e32 v44, 16, v45
	v_and_b32_e32 v45, 0xffff0000, v45
	v_pk_fma_f32 v[46:47], v[120:121], v[46:47], v[98:99] op_sel_hi:[0,1,1]
	v_pk_mul_f32 v[42:43], v[48:49], v[42:43]
	v_pk_mul_f32 v[44:45], v[46:47], v[44:45]
	v_cvt_pk_bf16_f32 v42, v42, v43
	v_cvt_pk_bf16_f32 v43, v44, v45
	global_store_dwordx2 v[40:41], v[42:43], off offset:32
	v_add_u32_e32 v42, v167, v169
	ds_read_b64 v[42:43], v42
	v_add_u32_e32 v44, v165, v169
	v_add_u32_e32 v46, v167, v170
	v_add_u32_e32 v48, v165, v170
	ds_read_b64 v[44:45], v44
	ds_read_b64 v[46:47], v46
	ds_read_b64 v[48:49], v48
	s_waitcnt lgkmcnt(3)
	v_lshlrev_b32_e32 v50, 16, v42
	v_and_b32_e32 v51, 0xffff0000, v42
	s_waitcnt lgkmcnt(2)
	v_lshlrev_b32_e32 v52, 16, v44
	v_and_b32_e32 v53, 0xffff0000, v44
	v_lshlrev_b32_e32 v44, 16, v45
	v_and_b32_e32 v45, 0xffff0000, v45
	v_pk_fma_f32 v[52:53], v[120:121], v[52:53], v[88:89] op_sel_hi:[0,1,1]
	v_lshlrev_b32_e32 v42, 16, v43
	v_and_b32_e32 v43, 0xffff0000, v43
	v_pk_fma_f32 v[44:45], v[120:121], v[44:45], v[90:91] op_sel_hi:[0,1,1]
	v_pk_mul_f32 v[50:51], v[52:53], v[50:51]
	v_pk_mul_f32 v[42:43], v[44:45], v[42:43]
	v_cvt_pk_bf16_f32 v44, v50, v51
	v_cvt_pk_bf16_f32 v45, v42, v43
	global_store_dwordx2 v[40:41], v[44:45], off offset:64
	s_waitcnt lgkmcnt(0)
	v_lshlrev_b32_e32 v44, 16, v48
	v_and_b32_e32 v45, 0xffff0000, v48
	v_lshlrev_b32_e32 v42, 16, v46
	v_and_b32_e32 v43, 0xffff0000, v46
	v_pk_fma_f32 v[44:45], v[120:121], v[44:45], v[84:85] op_sel_hi:[0,1,1]
	v_pk_mul_f32 v[42:43], v[44:45], v[42:43]
	v_lshlrev_b32_e32 v44, 16, v47
	v_and_b32_e32 v45, 0xffff0000, v47
	v_lshlrev_b32_e32 v46, 16, v49
	v_and_b32_e32 v47, 0xffff0000, v49
	v_pk_fma_f32 v[46:47], v[120:121], v[46:47], v[86:87] op_sel_hi:[0,1,1]
	v_pk_mul_f32 v[44:45], v[46:47], v[44:45]
	v_cvt_pk_bf16_f32 v42, v42, v43
	v_cvt_pk_bf16_f32 v43, v44, v45
	global_store_dwordx2 v[40:41], v[42:43], off offset:96
	v_add_u32_e32 v42, v167, v171
	ds_read_b64 v[42:43], v42
	v_add_u32_e32 v44, v165, v171
	v_add_u32_e32 v46, v167, v172
	v_add_u32_e32 v48, v165, v172
	ds_read_b64 v[44:45], v44
	ds_read_b64 v[46:47], v46
	ds_read_b64 v[48:49], v48
	s_waitcnt lgkmcnt(3)
	v_lshlrev_b32_e32 v50, 16, v42
	v_and_b32_e32 v51, 0xffff0000, v42
	s_waitcnt lgkmcnt(2)
	v_lshlrev_b32_e32 v52, 16, v44
	v_and_b32_e32 v53, 0xffff0000, v44
	v_lshlrev_b32_e32 v44, 16, v45
	v_and_b32_e32 v45, 0xffff0000, v45
	v_pk_fma_f32 v[52:53], v[120:121], v[52:53], v[80:81] op_sel_hi:[0,1,1]
	v_lshlrev_b32_e32 v42, 16, v43
	v_and_b32_e32 v43, 0xffff0000, v43
	v_pk_fma_f32 v[44:45], v[120:121], v[44:45], v[82:83] op_sel_hi:[0,1,1]
	v_pk_mul_f32 v[50:51], v[52:53], v[50:51]
	v_pk_mul_f32 v[42:43], v[44:45], v[42:43]
	v_cvt_pk_bf16_f32 v44, v50, v51
	v_cvt_pk_bf16_f32 v45, v42, v43
	global_store_dwordx2 v[40:41], v[44:45], off offset:128
	s_waitcnt lgkmcnt(0)
	v_lshlrev_b32_e32 v44, 16, v48
	v_and_b32_e32 v45, 0xffff0000, v48
	v_lshlrev_b32_e32 v42, 16, v46
	v_and_b32_e32 v43, 0xffff0000, v46
	v_pk_fma_f32 v[44:45], v[120:121], v[44:45], v[72:73] op_sel_hi:[0,1,1]
	v_pk_mul_f32 v[42:43], v[44:45], v[42:43]
	v_lshlrev_b32_e32 v44, 16, v47
	v_and_b32_e32 v45, 0xffff0000, v47
	v_lshlrev_b32_e32 v46, 16, v49
	v_and_b32_e32 v47, 0xffff0000, v49
	v_pk_fma_f32 v[46:47], v[120:121], v[46:47], v[74:75] op_sel_hi:[0,1,1]
	v_pk_mul_f32 v[44:45], v[46:47], v[44:45]
	v_cvt_pk_bf16_f32 v42, v42, v43
	v_cvt_pk_bf16_f32 v43, v44, v45
	global_store_dwordx2 v[40:41], v[42:43], off offset:160
	v_add_u32_e32 v42, v167, v173
	ds_read_b64 v[42:43], v42
	v_add_u32_e32 v44, v165, v173
	v_add_u32_e32 v46, v167, v174
	v_add_u32_e32 v48, v165, v174
	ds_read_b64 v[44:45], v44
	ds_read_b64 v[46:47], v46
	ds_read_b64 v[48:49], v48
	s_waitcnt lgkmcnt(3)
	v_lshlrev_b32_e32 v50, 16, v42
	v_and_b32_e32 v51, 0xffff0000, v42
	s_waitcnt lgkmcnt(2)
	v_lshlrev_b32_e32 v52, 16, v44
	v_and_b32_e32 v53, 0xffff0000, v44
	v_lshlrev_b32_e32 v44, 16, v45
	v_and_b32_e32 v45, 0xffff0000, v45
	v_pk_fma_f32 v[52:53], v[120:121], v[52:53], v[60:61] op_sel_hi:[0,1,1]
	v_lshlrev_b32_e32 v42, 16, v43
	v_and_b32_e32 v43, 0xffff0000, v43
	v_pk_fma_f32 v[44:45], v[120:121], v[44:45], v[62:63] op_sel_hi:[0,1,1]
	v_pk_mul_f32 v[50:51], v[52:53], v[50:51]
	v_pk_mul_f32 v[42:43], v[44:45], v[42:43]
	v_cvt_pk_bf16_f32 v44, v50, v51
	v_cvt_pk_bf16_f32 v45, v42, v43
	global_store_dwordx2 v[40:41], v[44:45], off offset:192
	s_waitcnt lgkmcnt(0)
	v_lshlrev_b32_e32 v44, 16, v48
	v_and_b32_e32 v45, 0xffff0000, v48
	v_lshlrev_b32_e32 v42, 16, v46
	v_and_b32_e32 v43, 0xffff0000, v46
	v_pk_fma_f32 v[36:37], v[120:121], v[44:45], v[36:37] op_sel_hi:[0,1,1]
	v_lshlrev_b32_e32 v44, 16, v49
	v_and_b32_e32 v45, 0xffff0000, v49
	v_pk_mul_f32 v[36:37], v[36:37], v[42:43]
	v_lshlrev_b32_e32 v42, 16, v47
	v_and_b32_e32 v43, 0xffff0000, v47
	v_pk_fma_f32 v[38:39], v[120:121], v[44:45], v[38:39] op_sel_hi:[0,1,1]
	v_pk_mul_f32 v[38:39], v[38:39], v[42:43]
	v_cvt_pk_bf16_f32 v36, v36, v37
	v_cvt_pk_bf16_f32 v37, v38, v39
	global_store_dwordx2 v[40:41], v[36:37], off offset:224
	s_barrier
	s_cbranch_scc1 .LBB0_860
.LBB0_794:
	ds_write_b128 v176, v[0:3]
	s_and_saveexec_b64 s[28:29], s[4:5]
	v_mov_b32_e32 v36, s46
	ds_write_b128 v36, v[200:203]
	s_or_b64 exec, exec, s[28:29]
	s_add_i32 s34, s15, s14
	v_readlane_b32 s56, v248, 8
	s_ashr_i32 s35, s34, 31
	v_readlane_b32 s57, v248, 9
	s_lshl_b64 s[42:43], s[34:35], 2
	v_readlane_b32 s58, v248, 10
	v_readlane_b32 s59, v248, 11
	s_mov_b64 s[48:49], s[56:57]
	s_add_u32 s36, s48, s42
	s_mov_b64 s[50:51], s[58:59]
	s_addc_u32 s37, s49, s43
	s_add_u32 s40, s50, s42
	global_load_dword v38, v177, s[36:37]
	global_load_dword v40, v129, s[36:37]
	global_load_dword v36, v178, s[36:37]
	s_addc_u32 s41, s51, s43
	global_load_dword v42, v129, s[40:41]
	v_and_b32_e32 v46, 0xffff0000, v5
	v_and_b32_e32 v48, 0xffff0000, v4
	v_and_b32_e32 v66, 0xffff0000, v9
	v_and_b32_e32 v45, 16, v7
	v_and_b32_e32 v44, 0xffff0000, v6
	v_and_b32_e32 v47, 16, v6
	v_lshlrev_b32_e32 v57, 16, v6
	v_and_b32_e32 v49, 16, v5
	v_lshlrev_b32_e32 v59, 16, v5
	v_lshlrev_b32_e32 v61, 16, v4
	v_lshlrev_b32_e32 v60, 16, v195
	v_and_b32_e32 v51, 16, v11
	v_and_b32_e32 v50, 0xffff0000, v10
	v_lshlrev_b32_e32 v69, 16, v10
	v_mov_b32_e32 v56, v46
	v_mov_b32_e32 v58, v48
	v_mov_b32_e32 v68, v66
	v_mov_b32_e32 v52, v44
	v_pk_mov_b32 v[76:77], v[60:61], v[48:49] op_sel:[1,0]
	v_mov_b32_e32 v62, v50
	v_pk_mov_b32 v[80:81], v[58:59], v[46:47] op_sel:[1,0]
	v_pk_mov_b32 v[82:83], v[56:57], v[44:45] op_sel:[1,0]
	v_pk_mov_b32 v[86:87], v[68:69], v[50:51] op_sel:[1,0]
	global_load_dword v48, v180, s[36:37]
	global_load_dword v44, v181, s[36:37]
	global_load_dword v50, v179, s[36:37]
	global_load_dword v46, v179, s[40:41]
	v_lshlrev_b32_e32 v53, 16, v7
	v_and_b32_e32 v55, 0xffff0000, v195
	v_and_b32_e32 v54, 0xffff0000, v7
	v_and_b32_e32 v70, 0xffff0000, v8
	v_and_b32_e32 v67, 16, v10
	v_and_b32_e32 v71, 16, v9
	v_lshlrev_b32_e32 v73, 16, v9
	v_lshlrev_b32_e32 v75, 16, v8
	v_lshlrev_b32_e32 v74, 16, v194
	v_mov_b32_e32 v72, v70
	v_pk_mov_b32 v[78:79], v[52:53], v[54:55] op_sel:[1,0]
	v_pk_mov_b32 v[70:71], v[74:75], v[70:71] op_sel:[1,0]
	v_pk_mov_b32 v[66:67], v[72:73], v[66:67] op_sel:[1,0]
	v_add_u32_e32 v37, v145, v160
	v_lshlrev_b32_e32 v63, 16, v11
	v_and_b32_e32 v65, 0xffff0000, v194
	v_and_b32_e32 v64, 0xffff0000, v11
	v_pk_mov_b32 v[84:85], v[62:63], v[64:65] op_sel:[1,0]
	v_add_u32_e32 v142, v163, v160
	v_add_u32_e32 v148, v163, v161
	v_add_u32_e32 v199, v163, v162
	s_lshl_b64 s[30:31], s[34:35], 15
	v_mov_b32_e32 v147, 0
	v_mov_b32_e32 v153, 0
	v_readlane_b32 s60, v248, 12
	v_readlane_b32 s61, v248, 13
	v_readlane_b32 s62, v248, 14
	v_readlane_b32 s63, v248, 15
	v_readlane_b32 s64, v248, 16
	v_readlane_b32 s65, v248, 17
	v_readlane_b32 s66, v248, 18
	v_readlane_b32 s67, v248, 19
	v_readlane_b32 s68, v248, 20
	v_readlane_b32 s69, v248, 21
	v_readlane_b32 s70, v248, 22
	v_readlane_b32 s71, v248, 23
	s_waitcnt vmcnt(7)
	v_pk_mul_f32 v[76:77], v[38:39], v[76:77] op_sel_hi:[0,1]
	v_pk_mul_f32 v[80:81], v[38:39], v[80:81] op_sel_hi:[0,1]
	v_pk_mul_f32 v[82:83], v[38:39], v[82:83] op_sel_hi:[0,1]
	v_pk_mul_f32 v[78:79], v[38:39], v[78:79] op_sel_hi:[0,1]
	v_pk_mul_f32 v[70:71], v[38:39], v[70:71] op_sel_hi:[0,1]
	v_pk_mul_f32 v[66:67], v[38:39], v[66:67] op_sel_hi:[0,1]
	s_waitcnt vmcnt(6)
	v_pk_fma_f32 v[60:61], v[40:41], v[60:61], v[76:77] op_sel_hi:[0,1,1]
	v_pk_fma_f32 v[76:77], v[40:41], v[58:59], v[80:81] op_sel_hi:[0,1,1]
	v_pk_fma_f32 v[80:81], v[40:41], v[56:57], v[82:83] op_sel_hi:[0,1,1]
	v_pk_fma_f32 v[78:79], v[40:41], v[52:53], v[78:79] op_sel_hi:[0,1,1]
	v_pk_mul_f32 v[86:87], v[38:39], v[86:87] op_sel_hi:[0,1]
	v_pk_fma_f32 v[70:71], v[40:41], v[74:75], v[70:71] op_sel_hi:[0,1,1]
	v_pk_fma_f32 v[66:67], v[40:41], v[72:73], v[66:67] op_sel_hi:[0,1,1]
	s_waitcnt vmcnt(5)
	v_pk_fma_f32 v[58:59], v[36:37], v[58:59], v[60:61] op_sel_hi:[0,1,1]
	v_pk_fma_f32 v[56:57], v[36:37], v[56:57], v[76:77] op_sel_hi:[0,1,1]
	v_pk_fma_f32 v[52:53], v[36:37], v[52:53], v[80:81] op_sel_hi:[0,1,1]
	v_pk_fma_f32 v[54:55], v[36:37], v[54:55], v[78:79] op_sel_hi:[0,1,1]
	v_pk_mul_f32 v[84:85], v[38:39], v[84:85] op_sel_hi:[0,1]
	v_pk_fma_f32 v[74:75], v[40:41], v[68:69], v[86:87] op_sel_hi:[0,1,1]
	v_pk_fma_f32 v[60:61], v[36:37], v[72:73], v[70:71] op_sel_hi:[0,1,1]
	v_pk_fma_f32 v[66:67], v[36:37], v[68:69], v[66:67] op_sel_hi:[0,1,1]
	s_waitcnt vmcnt(4)
	v_pk_add_f32 v[58:59], v[42:43], v[58:59] op_sel_hi:[0,1]
	v_pk_add_f32 v[56:57], v[42:43], v[56:57] op_sel_hi:[0,1]
	v_pk_add_f32 v[68:69], v[42:43], v[52:53] op_sel_hi:[0,1]
	v_pk_add_f32 v[70:71], v[42:43], v[54:55] op_sel_hi:[0,1]
	v_pk_fma_f32 v[82:83], v[40:41], v[62:63], v[84:85] op_sel_hi:[0,1,1]
	v_cvt_pk_bf16_f32 v52, v58, v59
	v_cvt_pk_bf16_f32 v53, v56, v57
	v_cvt_pk_bf16_f32 v54, v68, v69
	v_cvt_pk_bf16_f32 v55, v70, v71
	v_pk_fma_f32 v[62:63], v[36:37], v[62:63], v[74:75] op_sel_hi:[0,1,1]
	ds_write_b128 v37, v[52:55]
	v_pk_fma_f32 v[52:53], v[36:37], v[64:65], v[82:83] op_sel_hi:[0,1,1]
	v_pk_add_f32 v[60:61], v[42:43], v[60:61] op_sel_hi:[0,1]
	v_pk_add_f32 v[66:67], v[42:43], v[66:67] op_sel_hi:[0,1]
	v_pk_add_f32 v[62:63], v[42:43], v[62:63] op_sel_hi:[0,1]
	v_pk_add_f32 v[56:57], v[42:43], v[52:53] op_sel_hi:[0,1]
	v_cvt_pk_bf16_f32 v52, v60, v61
	v_cvt_pk_bf16_f32 v53, v66, v67
	v_cvt_pk_bf16_f32 v54, v62, v63
	v_cvt_pk_bf16_f32 v55, v56, v57
	v_add_u32_e32 v39, v145, v161
	v_and_b32_e32 v60, 0xffff0000, v13
	ds_write_b128 v39, v[52:55]
	v_and_b32_e32 v53, 16, v15
	v_and_b32_e32 v52, 0xffff0000, v14
	v_lshlrev_b32_e32 v63, 16, v14
	v_mov_b32_e32 v62, v60
	v_and_b32_e32 v64, 0xffff0000, v12
	v_mov_b32_e32 v54, v52
	v_and_b32_e32 v61, 16, v14
	v_lshlrev_b32_e32 v67, 16, v13
	v_mov_b32_e32 v66, v64
	v_pk_mov_b32 v[52:53], v[62:63], v[52:53] op_sel:[1,0]
	v_pk_mov_b32 v[60:61], v[66:67], v[60:61] op_sel:[1,0]
	v_pk_mul_f32 v[52:53], v[38:39], v[52:53] op_sel_hi:[0,1]
	v_lshlrev_b32_e32 v55, 16, v15
	v_and_b32_e32 v57, 0xffff0000, v193
	v_and_b32_e32 v56, 0xffff0000, v15
	v_and_b32_e32 v65, 16, v13
	v_lshlrev_b32_e32 v69, 16, v12
	v_lshlrev_b32_e32 v68, 16, v193
	v_pk_mul_f32 v[60:61], v[38:39], v[60:61] op_sel_hi:[0,1]
	v_pk_fma_f32 v[52:53], v[40:41], v[62:63], v[52:53] op_sel_hi:[0,1,1]
	v_pk_mov_b32 v[58:59], v[54:55], v[56:57] op_sel:[1,0]
	v_pk_mov_b32 v[64:65], v[68:69], v[64:65] op_sel:[1,0]
	v_pk_fma_f32 v[60:61], v[40:41], v[66:67], v[60:61] op_sel_hi:[0,1,1]
	v_pk_fma_f32 v[52:53], v[36:37], v[54:55], v[52:53] op_sel_hi:[0,1,1]
	v_pk_mul_f32 v[64:65], v[38:39], v[64:65] op_sel_hi:[0,1]
	v_pk_fma_f32 v[60:61], v[36:37], v[62:63], v[60:61] op_sel_hi:[0,1,1]
	v_pk_add_f32 v[62:63], v[42:43], v[52:53] op_sel_hi:[0,1]
	v_pk_mul_f32 v[52:53], v[38:39], v[58:59] op_sel_hi:[0,1]
	v_pk_fma_f32 v[64:65], v[40:41], v[68:69], v[64:65] op_sel_hi:[0,1,1]
	v_pk_fma_f32 v[52:53], v[40:41], v[54:55], v[52:53] op_sel_hi:[0,1,1]
	v_pk_fma_f32 v[64:65], v[36:37], v[66:67], v[64:65] op_sel_hi:[0,1,1]
	v_pk_fma_f32 v[52:53], v[36:37], v[56:57], v[52:53] op_sel_hi:[0,1,1]
	v_pk_add_f32 v[64:65], v[42:43], v[64:65] op_sel_hi:[0,1]
	v_pk_add_f32 v[60:61], v[42:43], v[60:61] op_sel_hi:[0,1]
	v_pk_add_f32 v[56:57], v[42:43], v[52:53] op_sel_hi:[0,1]
	v_cvt_pk_bf16_f32 v52, v64, v65
	v_cvt_pk_bf16_f32 v53, v60, v61
	v_cvt_pk_bf16_f32 v54, v62, v63
	v_cvt_pk_bf16_f32 v55, v56, v57
	ds_write_b128 v37, v[52:55] offset:16448
	v_and_b32_e32 v52, 0xffff0000, v18
	v_and_b32_e32 v60, 0xffff0000, v17
	v_and_b32_e32 v64, 0xffff0000, v16
	v_and_b32_e32 v53, 16, v19
	v_lshlrev_b32_e32 v55, 16, v19
	v_mov_b32_e32 v54, v52
	v_and_b32_e32 v57, 0xffff0000, v192
	v_and_b32_e32 v56, 0xffff0000, v19
	v_and_b32_e32 v61, 16, v18
	v_lshlrev_b32_e32 v63, 16, v18
	v_mov_b32_e32 v62, v60
	v_and_b32_e32 v65, 16, v17
	v_lshlrev_b32_e32 v67, 16, v17
	v_mov_b32_e32 v66, v64
	v_lshlrev_b32_e32 v69, 16, v16
	v_lshlrev_b32_e32 v68, 16, v192
	v_pk_mov_b32 v[58:59], v[54:55], v[56:57] op_sel:[1,0]
	v_pk_mov_b32 v[64:65], v[68:69], v[64:65] op_sel:[1,0]
	v_pk_mov_b32 v[60:61], v[66:67], v[60:61] op_sel:[1,0]
	v_pk_mov_b32 v[52:53], v[62:63], v[52:53] op_sel:[1,0]
	v_pk_mul_f32 v[64:65], v[38:39], v[64:65] op_sel_hi:[0,1]
	v_pk_mul_f32 v[60:61], v[38:39], v[60:61] op_sel_hi:[0,1]
	v_pk_mul_f32 v[52:53], v[38:39], v[52:53] op_sel_hi:[0,1]
	v_pk_mul_f32 v[38:39], v[38:39], v[58:59] op_sel_hi:[0,1]
	v_pk_fma_f32 v[64:65], v[40:41], v[68:69], v[64:65] op_sel_hi:[0,1,1]
	v_pk_fma_f32 v[60:61], v[40:41], v[66:67], v[60:61] op_sel_hi:[0,1,1]
	v_pk_fma_f32 v[52:53], v[40:41], v[62:63], v[52:53] op_sel_hi:[0,1,1]
	v_pk_fma_f32 v[38:39], v[40:41], v[54:55], v[38:39] op_sel_hi:[0,1,1]
	v_pk_fma_f32 v[64:65], v[36:37], v[66:67], v[64:65] op_sel_hi:[0,1,1]
	v_pk_fma_f32 v[60:61], v[36:37], v[62:63], v[60:61] op_sel_hi:[0,1,1]
	v_pk_fma_f32 v[52:53], v[36:37], v[54:55], v[52:53] op_sel_hi:[0,1,1]
	v_pk_fma_f32 v[36:37], v[36:37], v[56:57], v[38:39] op_sel_hi:[0,1,1]
	v_pk_add_f32 v[64:65], v[42:43], v[64:65] op_sel_hi:[0,1]
	v_pk_add_f32 v[60:61], v[42:43], v[60:61] op_sel_hi:[0,1]
	v_pk_add_f32 v[52:53], v[42:43], v[52:53] op_sel_hi:[0,1]
	v_pk_add_f32 v[40:41], v[42:43], v[36:37] op_sel_hi:[0,1]
	v_cvt_pk_bf16_f32 v36, v64, v65
	v_cvt_pk_bf16_f32 v37, v60, v61
	v_cvt_pk_bf16_f32 v38, v52, v53
	v_cvt_pk_bf16_f32 v39, v40, v41
	v_add_u32_e32 v40, v145, v162
	v_and_b32_e32 v52, 0xffff0000, v21
	ds_write_b128 v40, v[36:39]
	v_and_b32_e32 v37, 16, v23
	v_and_b32_e32 v36, 0xffff0000, v22
	v_lshlrev_b32_e32 v55, 16, v22
	v_mov_b32_e32 v54, v52
	v_and_b32_e32 v56, 0xffff0000, v20
	v_mov_b32_e32 v38, v36
	v_and_b32_e32 v53, 16, v22
	v_lshlrev_b32_e32 v59, 16, v21
	v_mov_b32_e32 v58, v56
	v_pk_mov_b32 v[36:37], v[54:55], v[36:37] op_sel:[1,0]
	v_pk_mov_b32 v[52:53], v[58:59], v[52:53] op_sel:[1,0]
	s_waitcnt vmcnt(3)
	v_pk_mul_f32 v[36:37], v[48:49], v[36:37] op_sel_hi:[0,1]
	v_lshlrev_b32_e32 v39, 16, v23
	v_and_b32_e32 v41, 0xffff0000, v191
	v_and_b32_e32 v40, 0xffff0000, v23
	v_and_b32_e32 v57, 16, v21
	v_lshlrev_b32_e32 v61, 16, v20
	v_lshlrev_b32_e32 v60, 16, v191
	v_pk_mul_f32 v[52:53], v[48:49], v[52:53] op_sel_hi:[0,1]
	s_waitcnt vmcnt(1)
	v_pk_fma_f32 v[36:37], v[50:51], v[54:55], v[36:37] op_sel_hi:[0,1,1]
	v_pk_mov_b32 v[42:43], v[38:39], v[40:41] op_sel:[1,0]
	v_pk_mov_b32 v[56:57], v[60:61], v[56:57] op_sel:[1,0]
	v_pk_fma_f32 v[52:53], v[50:51], v[58:59], v[52:53] op_sel_hi:[0,1,1]
	v_pk_fma_f32 v[36:37], v[44:45], v[38:39], v[36:37] op_sel_hi:[0,1,1]
	v_pk_mul_f32 v[56:57], v[48:49], v[56:57] op_sel_hi:[0,1]
	v_pk_fma_f32 v[52:53], v[44:45], v[54:55], v[52:53] op_sel_hi:[0,1,1]
	s_waitcnt vmcnt(0)
	v_pk_add_f32 v[54:55], v[46:47], v[36:37] op_sel_hi:[0,1]
	v_pk_mul_f32 v[36:37], v[48:49], v[42:43] op_sel_hi:[0,1]
	v_pk_fma_f32 v[56:57], v[50:51], v[60:61], v[56:57] op_sel_hi:[0,1,1]
	v_pk_fma_f32 v[36:37], v[50:51], v[38:39], v[36:37] op_sel_hi:[0,1,1]
	v_pk_fma_f32 v[56:57], v[44:45], v[58:59], v[56:57] op_sel_hi:[0,1,1]
	v_pk_fma_f32 v[36:37], v[44:45], v[40:41], v[36:37] op_sel_hi:[0,1,1]
	v_pk_add_f32 v[56:57], v[46:47], v[56:57] op_sel_hi:[0,1]
	v_pk_add_f32 v[52:53], v[46:47], v[52:53] op_sel_hi:[0,1]
	v_pk_add_f32 v[40:41], v[46:47], v[36:37] op_sel_hi:[0,1]
	v_cvt_pk_bf16_f32 v36, v56, v57
	v_cvt_pk_bf16_f32 v37, v52, v53
	v_cvt_pk_bf16_f32 v38, v54, v55
	v_cvt_pk_bf16_f32 v39, v40, v41
	v_and_b32_e32 v52, 0xffff0000, v25
	ds_write_b128 v142, v[36:39]
	v_and_b32_e32 v37, 16, v27
	v_and_b32_e32 v36, 0xffff0000, v26
	v_lshlrev_b32_e32 v55, 16, v26
	v_mov_b32_e32 v54, v52
	v_and_b32_e32 v56, 0xffff0000, v24
	v_mov_b32_e32 v38, v36
	v_and_b32_e32 v53, 16, v26
	v_lshlrev_b32_e32 v59, 16, v25
	v_mov_b32_e32 v58, v56
	v_pk_mov_b32 v[36:37], v[54:55], v[36:37] op_sel:[1,0]
	v_pk_mov_b32 v[52:53], v[58:59], v[52:53] op_sel:[1,0]
	v_pk_mul_f32 v[36:37], v[48:49], v[36:37] op_sel_hi:[0,1]
	v_lshlrev_b32_e32 v39, 16, v27
	v_and_b32_e32 v41, 0xffff0000, v190
	v_and_b32_e32 v40, 0xffff0000, v27
	v_and_b32_e32 v57, 16, v25
	v_lshlrev_b32_e32 v61, 16, v24
	v_lshlrev_b32_e32 v60, 16, v190
	v_pk_mul_f32 v[52:53], v[48:49], v[52:53] op_sel_hi:[0,1]
	v_pk_fma_f32 v[36:37], v[50:51], v[54:55], v[36:37] op_sel_hi:[0,1,1]
	v_pk_mov_b32 v[42:43], v[38:39], v[40:41] op_sel:[1,0]
	v_pk_mov_b32 v[56:57], v[60:61], v[56:57] op_sel:[1,0]
	v_pk_fma_f32 v[52:53], v[50:51], v[58:59], v[52:53] op_sel_hi:[0,1,1]
	v_pk_fma_f32 v[36:37], v[44:45], v[38:39], v[36:37] op_sel_hi:[0,1,1]
	v_pk_mul_f32 v[56:57], v[48:49], v[56:57] op_sel_hi:[0,1]
	v_pk_fma_f32 v[52:53], v[44:45], v[54:55], v[52:53] op_sel_hi:[0,1,1]
	v_pk_add_f32 v[54:55], v[46:47], v[36:37] op_sel_hi:[0,1]
	v_pk_mul_f32 v[36:37], v[48:49], v[42:43] op_sel_hi:[0,1]
	v_pk_fma_f32 v[56:57], v[50:51], v[60:61], v[56:57] op_sel_hi:[0,1,1]
	v_pk_fma_f32 v[36:37], v[50:51], v[38:39], v[36:37] op_sel_hi:[0,1,1]
	v_pk_fma_f32 v[56:57], v[44:45], v[58:59], v[56:57] op_sel_hi:[0,1,1]
	v_pk_fma_f32 v[36:37], v[44:45], v[40:41], v[36:37] op_sel_hi:[0,1,1]
	v_pk_add_f32 v[56:57], v[46:47], v[56:57] op_sel_hi:[0,1]
	v_pk_add_f32 v[52:53], v[46:47], v[52:53] op_sel_hi:[0,1]
	v_pk_add_f32 v[40:41], v[46:47], v[36:37] op_sel_hi:[0,1]
	v_cvt_pk_bf16_f32 v36, v56, v57
	v_cvt_pk_bf16_f32 v37, v52, v53
	v_cvt_pk_bf16_f32 v38, v54, v55
	v_cvt_pk_bf16_f32 v39, v40, v41
	v_and_b32_e32 v52, 0xffff0000, v29
	ds_write_b128 v148, v[36:39]
	v_and_b32_e32 v37, 16, v31
	v_and_b32_e32 v36, 0xffff0000, v30
	v_lshlrev_b32_e32 v55, 16, v30
	v_mov_b32_e32 v54, v52
	v_and_b32_e32 v56, 0xffff0000, v28
	v_mov_b32_e32 v38, v36
	v_and_b32_e32 v53, 16, v30
	v_lshlrev_b32_e32 v59, 16, v29
	v_mov_b32_e32 v58, v56
	v_pk_mov_b32 v[36:37], v[54:55], v[36:37] op_sel:[1,0]
	v_pk_mov_b32 v[52:53], v[58:59], v[52:53] op_sel:[1,0]
	v_pk_mul_f32 v[36:37], v[48:49], v[36:37] op_sel_hi:[0,1]
	v_lshlrev_b32_e32 v39, 16, v31
	v_and_b32_e32 v41, 0xffff0000, v189
	v_and_b32_e32 v40, 0xffff0000, v31
	v_and_b32_e32 v57, 16, v29
	v_lshlrev_b32_e32 v61, 16, v28
	v_lshlrev_b32_e32 v60, 16, v189
	v_pk_mul_f32 v[52:53], v[48:49], v[52:53] op_sel_hi:[0,1]
	v_pk_fma_f32 v[36:37], v[50:51], v[54:55], v[36:37] op_sel_hi:[0,1,1]
	v_pk_mov_b32 v[42:43], v[38:39], v[40:41] op_sel:[1,0]
	v_pk_mov_b32 v[56:57], v[60:61], v[56:57] op_sel:[1,0]
	v_pk_fma_f32 v[52:53], v[50:51], v[58:59], v[52:53] op_sel_hi:[0,1,1]
	v_pk_fma_f32 v[36:37], v[44:45], v[38:39], v[36:37] op_sel_hi:[0,1,1]
	v_pk_mul_f32 v[56:57], v[48:49], v[56:57] op_sel_hi:[0,1]
	v_pk_fma_f32 v[52:53], v[44:45], v[54:55], v[52:53] op_sel_hi:[0,1,1]
	v_pk_add_f32 v[54:55], v[46:47], v[36:37] op_sel_hi:[0,1]
	v_pk_mul_f32 v[36:37], v[48:49], v[42:43] op_sel_hi:[0,1]
	v_pk_fma_f32 v[56:57], v[50:51], v[60:61], v[56:57] op_sel_hi:[0,1,1]
	v_pk_fma_f32 v[36:37], v[50:51], v[38:39], v[36:37] op_sel_hi:[0,1,1]
	v_pk_fma_f32 v[56:57], v[44:45], v[58:59], v[56:57] op_sel_hi:[0,1,1]
	v_pk_fma_f32 v[36:37], v[44:45], v[40:41], v[36:37] op_sel_hi:[0,1,1]
	v_pk_add_f32 v[56:57], v[46:47], v[56:57] op_sel_hi:[0,1]
	v_pk_add_f32 v[52:53], v[46:47], v[52:53] op_sel_hi:[0,1]
	v_pk_add_f32 v[40:41], v[46:47], v[36:37] op_sel_hi:[0,1]
	v_cvt_pk_bf16_f32 v36, v56, v57
	v_cvt_pk_bf16_f32 v37, v52, v53
	v_cvt_pk_bf16_f32 v38, v54, v55
	v_cvt_pk_bf16_f32 v39, v40, v41
	v_and_b32_e32 v52, 0xffff0000, v33
	ds_write_b128 v142, v[36:39] offset:16448
	v_and_b32_e32 v37, 16, v35
	v_and_b32_e32 v36, 0xffff0000, v34
	v_lshlrev_b32_e32 v55, 16, v34
	v_mov_b32_e32 v54, v52
	v_and_b32_e32 v56, 0xffff0000, v32
	v_mov_b32_e32 v38, v36
	v_and_b32_e32 v53, 16, v34
	v_lshlrev_b32_e32 v59, 16, v33
	v_mov_b32_e32 v58, v56
	v_pk_mov_b32 v[36:37], v[54:55], v[36:37] op_sel:[1,0]
	v_pk_mov_b32 v[52:53], v[58:59], v[52:53] op_sel:[1,0]
	v_pk_mul_f32 v[36:37], v[48:49], v[36:37] op_sel_hi:[0,1]
	v_lshlrev_b32_e32 v39, 16, v35
	v_and_b32_e32 v41, 0xffff0000, v196
	v_and_b32_e32 v40, 0xffff0000, v35
	v_and_b32_e32 v57, 16, v33
	v_lshlrev_b32_e32 v61, 16, v32
	v_lshlrev_b32_e32 v60, 16, v196
	v_pk_mul_f32 v[52:53], v[48:49], v[52:53] op_sel_hi:[0,1]
	v_pk_fma_f32 v[36:37], v[50:51], v[54:55], v[36:37] op_sel_hi:[0,1,1]
	v_pk_mov_b32 v[42:43], v[38:39], v[40:41] op_sel:[1,0]
	v_pk_mov_b32 v[56:57], v[60:61], v[56:57] op_sel:[1,0]
	v_pk_fma_f32 v[52:53], v[50:51], v[58:59], v[52:53] op_sel_hi:[0,1,1]
	v_pk_fma_f32 v[36:37], v[44:45], v[38:39], v[36:37] op_sel_hi:[0,1,1]
	v_pk_mul_f32 v[56:57], v[48:49], v[56:57] op_sel_hi:[0,1]
	v_pk_fma_f32 v[52:53], v[44:45], v[54:55], v[52:53] op_sel_hi:[0,1,1]
	v_pk_add_f32 v[54:55], v[46:47], v[36:37] op_sel_hi:[0,1]
	v_pk_mul_f32 v[36:37], v[48:49], v[42:43] op_sel_hi:[0,1]
	v_pk_fma_f32 v[56:57], v[50:51], v[60:61], v[56:57] op_sel_hi:[0,1,1]
	v_pk_fma_f32 v[36:37], v[50:51], v[38:39], v[36:37] op_sel_hi:[0,1,1]
	v_pk_fma_f32 v[56:57], v[44:45], v[58:59], v[56:57] op_sel_hi:[0,1,1]
	v_pk_fma_f32 v[36:37], v[44:45], v[40:41], v[36:37] op_sel_hi:[0,1,1]
	v_pk_add_f32 v[56:57], v[46:47], v[56:57] op_sel_hi:[0,1]
	v_pk_add_f32 v[52:53], v[46:47], v[52:53] op_sel_hi:[0,1]
	v_pk_add_f32 v[40:41], v[46:47], v[36:37] op_sel_hi:[0,1]
	v_cvt_pk_bf16_f32 v36, v56, v57
	v_cvt_pk_bf16_f32 v37, v52, v53
	v_cvt_pk_bf16_f32 v38, v54, v55
	v_cvt_pk_bf16_f32 v39, v40, v41
	ds_write_b128 v199, v[36:39]
	s_waitcnt lgkmcnt(0)
	s_barrier
	ds_read_b128 v[36:39], v187
	ds_read_b128 v[40:43], v186
	s_waitcnt lgkmcnt(1)
	v_pk_mov_b32 v[50:51], v[36:37], v[38:39] op_sel:[1,0]
	s_waitcnt lgkmcnt(0)
	v_pk_mov_b32 v[48:49], v[42:43], v[36:37] op_sel:[1,0]
	v_perm_b32 v44, v43, v36, s47
	v_perm_b32 v45, v36, v37, s47
	ds_write_b128 v175, v[48:51] offset:16448
	v_perm_b32 v50, v42, v43, s47
	ds_write_b128 v175, v[36:39]
	v_perm_b32 v46, v37, v38, s47
	v_perm_b32 v47, v38, v39, s47
	v_mov_b32_e32 v54, v36
	v_mov_b32_e32 v55, v37
	v_perm_b32 v36, v41, v42, s47
	v_mov_b32_e32 v37, v50
	v_mov_b32_e32 v38, v44
	v_mov_b32_e32 v39, v45
	ds_write_b128 v175, v[36:39] offset:41120
	v_mov_b32_e32 v39, v36
	v_lshl_add_u64 v[36:37], v[136:137], 0, s[30:31]
	ds_write_b128 v175, v[44:47] offset:8224
	v_mov_b32_e32 v51, v44
	v_mov_b32_e32 v52, v45
	v_mov_b32_e32 v53, v46
	v_pk_mov_b32 v[46:47], v[40:41], v[42:43] op_sel:[1,0]
	v_perm_b32 v38, v40, v41, s47
	v_mov_b32_e32 v40, v50
	v_mov_b32_e32 v41, v44
	v_lshl_add_u64 v[36:37], v[36:37], 0, s[16:17]
	ds_write_b128 v175, v[50:53] offset:24672
	v_mov_b32_e32 v52, v42
	v_mov_b32_e32 v53, v43
	ds_write_b128 v175, v[38:41] offset:57568
	v_lshl_add_u64 v[38:39], v[36:37], 0, v[128:129]
	ds_write_b128 v175, v[52:55] offset:32896
	ds_write_b128 v175, v[46:49] offset:49344
	s_waitcnt lgkmcnt(0)
	s_barrier
	global_load_dwordx4 v[48:51], v[38:39], off nt
	s_and_saveexec_b64 s[28:29], s[0:1]
	s_cbranch_execz .LBB0_798
	global_load_short_d16_hi v153, v[38:39], off offset:-2
.LBB0_798:
	s_or_b64 exec, exec, s[28:29]
	s_and_saveexec_b64 s[28:29], s[10:11]
	s_cbranch_execz .LBB0_800
	global_load_short_d16_hi v147, v[38:39], off offset:16
.LBB0_800:
	s_or_b64 exec, exec, s[28:29]
	v_mov_b32_e32 v131, v129
	v_lshl_add_u64 v[40:41], v[36:37], 0, v[130:131]
	global_load_dwordx4 v[44:47], v[40:41], off nt
	v_mov_b32_e32 v155, 0
	v_mov_b32_e32 v159, 0
	s_and_saveexec_b64 s[28:29], s[0:1]
	s_cbranch_execz .LBB0_802
	global_load_short_d16_hi v159, v[40:41], off offset:-2
.LBB0_802:
	s_or_b64 exec, exec, s[28:29]
	s_and_saveexec_b64 s[28:29], s[10:11]
	s_cbranch_execz .LBB0_804
	global_load_short_d16_hi v155, v[40:41], off offset:16
.LBB0_804:
	s_or_b64 exec, exec, s[28:29]
	v_add_co_u32_e32 v40, vcc, 0x4000, v38
	v_mov_b32_e32 v151, 0
	s_nop 0
	v_addc_co_u32_e32 v41, vcc, 0, v39, vcc
	global_load_dwordx4 v[40:43], v[40:41], off nt
	v_mov_b32_e32 v157, 0
	s_and_saveexec_b64 s[28:29], s[0:1]
	s_cbranch_execz .LBB0_806
	v_add_co_u32_e32 v52, vcc, 0x3000, v38
	s_nop 1
	v_addc_co_u32_e32 v53, vcc, 0, v39, vcc
	global_load_short_d16_hi v157, v[52:53], off offset:4094
.LBB0_806:
	s_or_b64 exec, exec, s[28:29]
	s_and_saveexec_b64 s[28:29], s[10:11]
	s_cbranch_execz .LBB0_808
	v_add_co_u32_e32 v38, vcc, 0x4000, v38
	s_nop 1
	v_addc_co_u32_e32 v39, vcc, 0, v39, vcc
	global_load_short_d16_hi v151, v[38:39], off offset:16
.LBB0_808:
	s_or_b64 exec, exec, s[28:29]
	v_mov_b32_e32 v133, v129
	v_lshl_add_u64 v[52:53], v[36:37], 0, v[132:133]
	global_load_dwordx4 v[36:39], v[52:53], off nt
	v_mov_b32_e32 v143, 0
	v_mov_b32_e32 v149, 0
	s_and_saveexec_b64 s[28:29], s[0:1]
	s_cbranch_execz .LBB0_810
	global_load_short_d16_hi v149, v[52:53], off offset:-2
.LBB0_810:
	s_or_b64 exec, exec, s[28:29]
	s_and_saveexec_b64 s[28:29], s[10:11]
	s_cbranch_execz .LBB0_812
	global_load_short_d16_hi v143, v[52:53], off offset:16

.LBB0_818:
	s_waitcnt vmcnt(0)
	s_add_u32 s42, s38, s42
	s_addc_u32 s43, s39, s43
	s_waitcnt lgkmcnt(0)
	global_load_dword v60, v129, s[42:43]
	v_add_u32_e32 v122, v167, v134
	v_add_u32_e32 v121, v165, v134
	ds_read2_b64 v[62:65], v122 offset1:4
	ds_read2_b64 v[66:69], v121 offset1:4
	ds_read2_b64 v[70:73], v122 offset0:8 offset1:12
	ds_read2_b64 v[74:77], v121 offset0:8 offset1:12
	ds_read2_b64 v[84:87], v122 offset0:16 offset1:20
	ds_read2_b64 v[88:91], v121 offset0:16 offset1:20
	global_load_dword v120, v179, s[42:43]
	s_waitcnt lgkmcnt(4)
	v_lshlrev_b32_e32 v104, 16, v66
	v_and_b32_e32 v105, 0xffff0000, v66
	v_lshlrev_b32_e32 v66, 16, v67
	v_and_b32_e32 v67, 0xffff0000, v67
	v_lshlrev_b32_e32 v78, 16, v62
	v_and_b32_e32 v79, 0xffff0000, v62
	v_lshlrev_b32_e32 v62, 16, v63
	v_and_b32_e32 v63, 0xffff0000, v63
	s_waitcnt lgkmcnt(2)
	v_lshlrev_b32_e32 v204, 16, v74
	v_and_b32_e32 v205, 0xffff0000, v74
	v_lshlrev_b32_e32 v74, 16, v75
	v_and_b32_e32 v75, 0xffff0000, v75
	v_lshlrev_b32_e32 v208, 16, v76
	v_and_b32_e32 v209, 0xffff0000, v76
	v_lshlrev_b32_e32 v124, 16, v68
	v_and_b32_e32 v125, 0xffff0000, v68
	v_lshlrev_b32_e32 v68, 16, v69
	v_and_b32_e32 v69, 0xffff0000, v69
	v_lshlrev_b32_e32 v126, 16, v70
	v_and_b32_e32 v127, 0xffff0000, v70
	v_lshlrev_b32_e32 v70, 16, v71
	v_and_b32_e32 v71, 0xffff0000, v71
	v_lshlrev_b32_e32 v206, 16, v72
	v_and_b32_e32 v207, 0xffff0000, v72
	s_waitcnt lgkmcnt(0)
	v_lshlrev_b32_e32 v216, 16, v90
	v_and_b32_e32 v217, 0xffff0000, v90
	v_lshlrev_b32_e32 v106, 16, v64
	v_and_b32_e32 v107, 0xffff0000, v64
	v_lshlrev_b32_e32 v64, 16, v65
	v_and_b32_e32 v65, 0xffff0000, v65
	v_lshlrev_b32_e32 v76, 16, v77
	v_and_b32_e32 v77, 0xffff0000, v77
	v_lshlrev_b32_e32 v212, 16, v88
	v_and_b32_e32 v213, 0xffff0000, v88
	v_lshlrev_b32_e32 v88, 16, v89
	v_and_b32_e32 v89, 0xffff0000, v89
	v_lshlrev_b32_e32 v214, 16, v86
	v_and_b32_e32 v215, 0xffff0000, v86
	v_lshlrev_b32_e32 v72, 16, v73
	v_and_b32_e32 v73, 0xffff0000, v73
	v_lshlrev_b32_e32 v210, 16, v84
	v_and_b32_e32 v211, 0xffff0000, v84
	v_lshlrev_b32_e32 v84, 16, v85
	v_and_b32_e32 v85, 0xffff0000, v85
	s_waitcnt vmcnt(1)
	v_pk_fma_f32 v[104:105], v[60:61], v[104:105], v[116:117] op_sel_hi:[0,1,1]
	v_pk_fma_f32 v[66:67], v[60:61], v[66:67], v[118:119] op_sel_hi:[0,1,1]
	v_pk_fma_f32 v[74:75], v[60:61], v[74:75], v[98:99] op_sel_hi:[0,1,1]
	v_pk_fma_f32 v[98:99], v[60:61], v[208:209], v[108:109] op_sel_hi:[0,1,1]
	v_pk_mul_f32 v[78:79], v[104:105], v[78:79]
	v_pk_mul_f32 v[62:63], v[66:67], v[62:63]
	v_pk_fma_f32 v[100:101], v[60:61], v[124:125], v[100:101] op_sel_hi:[0,1,1]
	v_pk_fma_f32 v[68:69], v[60:61], v[68:69], v[102:103] op_sel_hi:[0,1,1]
	v_pk_fma_f32 v[96:97], v[60:61], v[204:205], v[96:97] op_sel_hi:[0,1,1]
	v_pk_mul_f32 v[70:71], v[74:75], v[70:71]
	v_pk_mul_f32 v[74:75], v[98:99], v[206:207]
	v_cvt_pk_bf16_f32 v78, v78, v79
	v_cvt_pk_bf16_f32 v79, v62, v63
	v_pk_fma_f32 v[62:63], v[60:61], v[216:217], v[92:93] op_sel_hi:[0,1,1]
	v_pk_fma_f32 v[76:77], v[60:61], v[76:77], v[110:111] op_sel_hi:[0,1,1]
	v_pk_fma_f32 v[102:103], v[60:61], v[212:213], v[112:113] op_sel_hi:[0,1,1]
	v_pk_fma_f32 v[88:89], v[60:61], v[88:89], v[114:115] op_sel_hi:[0,1,1]
	v_pk_mul_f32 v[66:67], v[100:101], v[106:107]
	v_pk_mul_f32 v[64:65], v[68:69], v[64:65]
	v_pk_mul_f32 v[68:69], v[96:97], v[126:127]
	v_cvt_pk_bf16_f32 v97, v70, v71
	v_cvt_pk_bf16_f32 v70, v74, v75
	v_pk_mul_f32 v[74:75], v[62:63], v[214:215]
	v_lshlrev_b32_e32 v62, 16, v91
	v_and_b32_e32 v63, 0xffff0000, v91
	v_pk_mul_f32 v[72:73], v[76:77], v[72:73]
	v_pk_mul_f32 v[76:77], v[102:103], v[210:211]
	v_pk_mul_f32 v[84:85], v[88:89], v[84:85]
	v_cvt_pk_bf16_f32 v88, v66, v67
	v_cvt_pk_bf16_f32 v96, v68, v69
	v_lshlrev_b32_e32 v66, 16, v87
	v_and_b32_e32 v67, 0xffff0000, v87
	v_pk_fma_f32 v[68:69], v[60:61], v[62:63], v[94:95] op_sel_hi:[0,1,1]
	v_cvt_pk_bf16_f32 v71, v72, v73
	v_cvt_pk_bf16_f32 v72, v76, v77
	v_pk_mul_f32 v[76:77], v[68:69], v[66:67]
	ds_read2_b64 v[66:69], v121 offset0:24 offset1:28
	v_cvt_pk_bf16_f32 v89, v64, v65
	ds_read2_b64 v[62:65], v122 offset0:24 offset1:28
	v_cvt_pk_bf16_f32 v73, v84, v85
	v_cvt_pk_bf16_f32 v74, v74, v75
	s_waitcnt lgkmcnt(1)
	v_lshlrev_b32_e32 v84, 16, v66
	v_and_b32_e32 v85, 0xffff0000, v66
	v_cvt_pk_bf16_f32 v75, v76, v77
	s_waitcnt lgkmcnt(0)
	v_lshlrev_b32_e32 v76, 16, v62
	v_and_b32_e32 v77, 0xffff0000, v62
	v_pk_fma_f32 v[80:81], v[60:61], v[84:85], v[80:81] op_sel_hi:[0,1,1]
	v_lshlrev_b32_e32 v66, 16, v67
	v_and_b32_e32 v67, 0xffff0000, v67
	v_pk_mul_f32 v[76:77], v[80:81], v[76:77]
	v_lshlrev_b32_e32 v62, 16, v63
	v_and_b32_e32 v63, 0xffff0000, v63
	v_pk_fma_f32 v[66:67], v[60:61], v[66:67], v[82:83] op_sel_hi:[0,1,1]
	v_pk_mul_f32 v[62:63], v[66:67], v[62:63]
	v_cvt_pk_bf16_f32 v66, v76, v77
	v_lshlrev_b32_e32 v76, 16, v68
	v_and_b32_e32 v77, 0xffff0000, v68
	v_cvt_pk_bf16_f32 v67, v62, v63
	v_lshlrev_b32_e32 v62, 16, v64
	v_and_b32_e32 v63, 0xffff0000, v64
	v_pk_fma_f32 v[56:57], v[60:61], v[76:77], v[56:57] op_sel_hi:[0,1,1]
	v_pk_mul_f32 v[56:57], v[56:57], v[62:63]
	v_lshlrev_b32_e32 v62, 16, v65
	v_and_b32_e32 v63, 0xffff0000, v65
	v_lshlrev_b32_e32 v64, 16, v69
	v_and_b32_e32 v65, 0xffff0000, v69
	v_pk_fma_f32 v[58:59], v[60:61], v[64:65], v[58:59] op_sel_hi:[0,1,1]
	v_pk_mul_f32 v[58:59], v[58:59], v[62:63]
	v_cvt_pk_bf16_f32 v56, v56, v57
	v_cvt_pk_bf16_f32 v57, v58, v59
	s_barrier
	ds_write2_b64 v182, v[78:79], v[88:89] offset1:4
	ds_write2_b64 v182, v[96:97], v[70:71] offset0:8 offset1:12
	ds_write2_b64 v182, v[72:73], v[74:75] offset0:16 offset1:20
	ds_write2_b64 v182, v[66:67], v[56:57] offset0:24 offset1:28
	ds_write_b128 v176, v[52:55]
	s_and_saveexec_b64 s[28:29], s[4:5]
	v_mov_b32_e32 v52, s46
	ds_write_b128 v52, v[200:203]
	s_or_b64 exec, exec, s[28:29]
	global_load_dword v57, v183, s[36:37]
	global_load_dword v56, v184, s[36:37]
	global_load_dword v54, v185, s[36:37]
	global_load_dword v52, v183, s[40:41]
	v_and_b32_e32 v64, 0xffff0000, v49
	v_lshlrev_b32_e32 v58, 16, v48
	v_and_b32_e32 v61, 0xffff0000, v51
	v_and_b32_e32 v63, 16, v51
	v_and_b32_e32 v62, 0xffff0000, v50
	v_lshlrev_b32_e32 v51, 16, v51
	v_and_b32_e32 v65, 16, v50
	v_lshlrev_b32_e32 v67, 16, v50
	v_and_b32_e32 v48, 0xffff0000, v48
	v_lshlrev_b32_e32 v49, 16, v49
	v_and_b32_e32 v74, 0xffff0000, v45
	v_mov_b32_e32 v66, v64
	v_lshlrev_b32_e32 v68, 16, v44
	v_and_b32_e32 v71, 0xffff0000, v47
	v_and_b32_e32 v73, 16, v47
	v_and_b32_e32 v72, 0xffff0000, v46
	v_lshlrev_b32_e32 v47, 16, v47
	v_and_b32_e32 v75, 16, v46
	v_lshlrev_b32_e32 v77, 16, v46
	v_and_b32_e32 v44, 0xffff0000, v44
	v_lshlrev_b32_e32 v45, 16, v45
	v_mov_b32_e32 v50, v62
	v_mov_b32_e32 v60, v51
	v_mov_b32_e32 v152, v48
	v_pk_mov_b32 v[64:65], v[48:49], v[64:65] op_sel:[1,0]
	v_mov_b32_e32 v76, v74
	v_pk_mov_b32 v[62:63], v[66:67], v[62:63] op_sel:[1,0]
	v_and_b32_e32 v59, 0xffff0000, v43
	v_mov_b32_e32 v146, v61
	v_mov_b32_e32 v46, v72
	v_mov_b32_e32 v70, v47
	v_mov_b32_e32 v158, v44
	v_pk_mov_b32 v[74:75], v[44:45], v[74:75] op_sel:[1,0]
	v_pk_mov_b32 v[72:73], v[76:77], v[72:73] op_sel:[1,0]
	v_lshlrev_b32_e32 v69, 16, v43
	v_mov_b32_e32 v154, v71
	v_lshlrev_b32_e32 v78, 16, v40
	v_and_b32_e32 v40, 0xffff0000, v40
	v_mov_b32_e32 v156, v40
	v_and_b32_e32 v81, 16, v43
	v_and_b32_e32 v80, 0xffff0000, v42
	v_lshlrev_b32_e32 v43, 16, v42
	v_mov_b32_e32 v150, v59
	s_add_i32 s15, s15, 1
	s_add_i32 s2, s34, 0x81
	s_cmp_lt_u32 s15, s54
	s_cselect_b32 s34, s2, 0x100000
	s_cmpk_gt_i32 s34, 0x47f
	s_waitcnt vmcnt(3)
	v_mov_b32_e32 v84, v57
	s_waitcnt vmcnt(2)
	v_pk_mul_f32 v[82:83], v[152:153], v[56:57]
	v_pk_mul_f32 v[64:65], v[56:57], v[64:65] op_sel_hi:[0,1]
	v_pk_mul_f32 v[62:63], v[56:57], v[62:63] op_sel_hi:[0,1]
	v_pk_mul_f32 v[60:61], v[56:57], v[60:61] op_sel_hi:[0,1]
	v_pk_mul_f32 v[86:87], v[158:159], v[56:57]
	v_pk_mul_f32 v[74:75], v[56:57], v[74:75] op_sel_hi:[0,1]
	v_pk_mul_f32 v[72:73], v[56:57], v[72:73] op_sel_hi:[0,1]
	v_pk_mul_f32 v[70:71], v[56:57], v[70:71] op_sel_hi:[0,1]
	v_pk_fma_f32 v[82:83], v[56:57], v[58:59], v[82:83] op_sel:[0,0,1] op_sel_hi:[1,0,0]
	v_pk_fma_f32 v[64:65], v[84:85], v[48:49], v[64:65] op_sel_hi:[0,1,1]
	v_pk_fma_f32 v[62:63], v[84:85], v[66:67], v[62:63] op_sel_hi:[0,1,1]
	v_pk_fma_f32 v[60:61], v[84:85], v[50:51], v[60:61] op_sel_hi:[0,1,1]
	v_pk_fma_f32 v[86:87], v[56:57], v[68:69], v[86:87] op_sel:[0,0,1] op_sel_hi:[1,0,0]
	v_pk_fma_f32 v[74:75], v[84:85], v[44:45], v[74:75] op_sel_hi:[0,1,1]
	v_pk_fma_f32 v[72:73], v[84:85], v[76:77], v[72:73] op_sel_hi:[0,1,1]
	v_pk_fma_f32 v[70:71], v[84:85], v[46:47], v[70:71] op_sel_hi:[0,1,1]
	s_waitcnt vmcnt(1)
	v_pk_fma_f32 v[48:49], v[54:55], v[48:49], v[82:83] op_sel_hi:[0,1,1]
	v_pk_fma_f32 v[64:65], v[54:55], v[66:67], v[64:65] op_sel_hi:[0,1,1]
	v_pk_fma_f32 v[50:51], v[54:55], v[50:51], v[62:63] op_sel_hi:[0,1,1]
	v_pk_fma_f32 v[60:61], v[54:55], v[146:147], v[60:61] op_sel_hi:[0,1,1]
	v_pk_fma_f32 v[44:45], v[54:55], v[44:45], v[86:87] op_sel_hi:[0,1,1]
	v_pk_fma_f32 v[62:63], v[54:55], v[76:77], v[74:75] op_sel_hi:[0,1,1]
	v_pk_fma_f32 v[46:47], v[54:55], v[46:47], v[72:73] op_sel_hi:[0,1,1]
	v_pk_fma_f32 v[66:67], v[54:55], v[154:155], v[70:71] op_sel_hi:[0,1,1]
	s_waitcnt vmcnt(0)
	v_pk_add_f32 v[48:49], v[52:53], v[48:49] op_sel_hi:[0,1]
	v_pk_add_f32 v[64:65], v[52:53], v[64:65] op_sel_hi:[0,1]
	v_pk_add_f32 v[50:51], v[52:53], v[50:51] op_sel_hi:[0,1]
	v_pk_add_f32 v[60:61], v[52:53], v[60:61] op_sel_hi:[0,1]
	v_pk_add_f32 v[70:71], v[52:53], v[44:45] op_sel_hi:[0,1]
	v_pk_add_f32 v[62:63], v[52:53], v[62:63] op_sel_hi:[0,1]
	v_pk_add_f32 v[72:73], v[52:53], v[46:47] op_sel_hi:[0,1]
	v_pk_add_f32 v[66:67], v[52:53], v[66:67] op_sel_hi:[0,1]
	v_cvt_pk_bf16_f32 v44, v48, v49
	v_cvt_pk_bf16_f32 v45, v64, v65
	v_cvt_pk_bf16_f32 v46, v50, v51
	v_cvt_pk_bf16_f32 v47, v60, v61
	v_cvt_pk_bf16_f32 v48, v70, v71
	v_cvt_pk_bf16_f32 v49, v62, v63
	v_cvt_pk_bf16_f32 v50, v72, v73
	v_cvt_pk_bf16_f32 v51, v66, v67
	ds_write_b128 v142, v[44:47]
	ds_write_b128 v148, v[48:51]
	v_and_b32_e32 v45, 16, v42
	v_and_b32_e32 v44, 0xffff0000, v41
	v_lshlrev_b32_e32 v41, 16, v41
	v_mov_b32_e32 v42, v44
	v_pk_mul_f32 v[46:47], v[156:157], v[56:57]
	v_pk_mov_b32 v[44:45], v[40:41], v[44:45] op_sel:[1,0]
	v_pk_fma_f32 v[46:47], v[56:57], v[78:79], v[46:47] op_sel:[0,0,1] op_sel_hi:[1,0,0]
	v_pk_mul_f32 v[44:45], v[56:57], v[44:45] op_sel_hi:[0,1]
	v_pk_fma_f32 v[46:47], v[54:55], v[40:41], v[46:47] op_sel_hi:[0,1,1]
	v_pk_fma_f32 v[40:41], v[84:85], v[40:41], v[44:45] op_sel_hi:[0,1,1]
	v_pk_fma_f32 v[40:41], v[54:55], v[42:43], v[40:41] op_sel_hi:[0,1,1]
	v_pk_add_f32 v[44:45], v[52:53], v[40:41] op_sel_hi:[0,1]
	v_pk_mov_b32 v[40:41], v[42:43], v[80:81] op_sel:[1,0]
	v_mov_b32_e32 v68, v80
	v_pk_mul_f32 v[40:41], v[56:57], v[40:41] op_sel_hi:[0,1]
	v_pk_fma_f32 v[40:41], v[84:85], v[42:43], v[40:41] op_sel_hi:[0,1,1]
	v_mov_b32_e32 v58, v69
	v_pk_fma_f32 v[40:41], v[54:55], v[68:69], v[40:41] op_sel_hi:[0,1,1]
	v_pk_add_f32 v[42:43], v[52:53], v[40:41] op_sel_hi:[0,1]
	v_pk_mul_f32 v[40:41], v[56:57], v[58:59] op_sel_hi:[0,1]
	v_pk_fma_f32 v[40:41], v[84:85], v[68:69], v[40:41] op_sel_hi:[0,1,1]
	v_pk_fma_f32 v[40:41], v[54:55], v[150:151], v[40:41] op_sel_hi:[0,1,1]
	v_pk_add_f32 v[46:47], v[52:53], v[46:47] op_sel_hi:[0,1]
	v_pk_add_f32 v[48:49], v[52:53], v[40:41] op_sel_hi:[0,1]
	v_cvt_pk_bf16_f32 v40, v46, v47
	v_cvt_pk_bf16_f32 v41, v44, v45
	v_cvt_pk_bf16_f32 v42, v42, v43
	v_cvt_pk_bf16_f32 v43, v48, v49
	ds_write_b128 v142, v[40:43] offset:16448
	v_lshlrev_b32_e32 v40, 16, v36
	v_and_b32_e32 v36, 0xffff0000, v36
	v_and_b32_e32 v49, 16, v38
	v_and_b32_e32 v48, 0xffff0000, v37
	v_lshlrev_b32_e32 v37, 16, v37
	v_mov_b32_e32 v148, v36
	v_and_b32_e32 v43, 0xffff0000, v39
	v_and_b32_e32 v45, 16, v39
	v_and_b32_e32 v44, 0xffff0000, v38
	v_lshlrev_b32_e32 v47, 16, v39
	v_lshlrev_b32_e32 v39, 16, v38
	v_mov_b32_e32 v38, v48
	v_pk_mul_f32 v[50:51], v[148:149], v[56:57]
	v_pk_mov_b32 v[48:49], v[36:37], v[48:49] op_sel:[1,0]
	v_pk_fma_f32 v[40:41], v[56:57], v[40:41], v[50:51] op_sel:[0,0,1] op_sel_hi:[1,0,0]
	v_pk_mul_f32 v[48:49], v[56:57], v[48:49] op_sel_hi:[0,1]
	v_pk_fma_f32 v[40:41], v[54:55], v[36:37], v[40:41] op_sel_hi:[0,1,1]
	v_pk_fma_f32 v[36:37], v[84:85], v[36:37], v[48:49] op_sel_hi:[0,1,1]
	v_pk_fma_f32 v[36:37], v[54:55], v[38:39], v[36:37] op_sel_hi:[0,1,1]
	v_pk_add_f32 v[48:49], v[52:53], v[36:37] op_sel_hi:[0,1]
	v_pk_mov_b32 v[36:37], v[38:39], v[44:45] op_sel:[1,0]
	v_mov_b32_e32 v46, v44
	v_pk_mul_f32 v[36:37], v[56:57], v[36:37] op_sel_hi:[0,1]
	v_pk_fma_f32 v[36:37], v[84:85], v[38:39], v[36:37] op_sel_hi:[0,1,1]
	v_mov_b32_e32 v42, v47
	v_pk_fma_f32 v[36:37], v[54:55], v[46:47], v[36:37] op_sel_hi:[0,1,1]
	v_pk_add_f32 v[38:39], v[52:53], v[36:37] op_sel_hi:[0,1]
	v_pk_mul_f32 v[36:37], v[56:57], v[42:43] op_sel_hi:[0,1]
	v_pk_fma_f32 v[36:37], v[84:85], v[46:47], v[36:37] op_sel_hi:[0,1,1]
	v_mov_b32_e32 v142, v43
	v_pk_fma_f32 v[36:37], v[54:55], v[142:143], v[36:37] op_sel_hi:[0,1,1]
	v_pk_add_f32 v[40:41], v[52:53], v[40:41] op_sel_hi:[0,1]
	v_pk_add_f32 v[42:43], v[52:53], v[36:37] op_sel_hi:[0,1]
	v_cvt_pk_bf16_f32 v36, v40, v41
	v_cvt_pk_bf16_f32 v37, v48, v49
	v_cvt_pk_bf16_f32 v38, v38, v39
	v_cvt_pk_bf16_f32 v39, v42, v43
	ds_write_b128 v199, v[36:39]
	s_waitcnt lgkmcnt(0)
	s_barrier
	ds_read_b128 v[36:39], v186
	ds_read_b128 v[40:43], v187
	s_waitcnt lgkmcnt(0)
	v_perm_b32 v44, v39, v40, s47
	v_perm_b32 v45, v40, v41, s47
	v_perm_b32 v46, v41, v42, s47
	v_pk_mov_b32 v[48:49], v[38:39], v[40:41] op_sel:[1,0]
	v_pk_mov_b32 v[50:51], v[40:41], v[42:43] op_sel:[1,0]
	ds_write_b128 v175, v[40:43]
	v_perm_b32 v47, v42, v43, s47
	ds_write_b128 v175, v[48:51] offset:16448
	v_perm_b32 v50, v38, v39, s47
	v_mov_b32_e32 v51, v44
	v_mov_b32_e32 v52, v45
	v_mov_b32_e32 v53, v46
	v_mov_b32_e32 v54, v40
	v_perm_b32 v40, v37, v38, s47
	ds_write_b128 v175, v[44:47] offset:8224
	ds_write_b128 v175, v[50:53] offset:24672
	v_mov_b32_e32 v52, v38
	v_mov_b32_e32 v53, v39
	v_mov_b32_e32 v55, v41
	v_mov_b32_e32 v41, v50
	v_mov_b32_e32 v42, v44
	v_mov_b32_e32 v43, v45
	v_pk_mov_b32 v[46:47], v[36:37], v[38:39] op_sel:[1,0]
	v_perm_b32 v36, v36, v37, s47
	v_mov_b32_e32 v37, v40
	v_mov_b32_e32 v38, v50
	v_mov_b32_e32 v39, v44
	ds_write_b128 v175, v[52:55] offset:32896
	ds_write_b128 v175, v[40:43] offset:41120
	ds_write_b128 v175, v[46:49] offset:49344
	ds_write_b128 v175, v[36:39] offset:57568
	s_waitcnt lgkmcnt(0)
	s_barrier
	s_cbranch_scc1 .LBB0_854
	s_add_i32 s12, s34, 0xffffff80
	s_ashr_i32 s13, s12, 31
	s_lshl_b64 s[28:29], s[12:13], 13
	s_lshl_b64 s[12:13], s[12:13], 15
	v_lshl_add_u64 v[0:1], v[138:139], 0, s[28:29]
	v_lshl_add_u64 v[16:17], v[136:137], 0, s[12:13]
	v_lshl_add_u64 v[18:19], v[16:17], 0, v[128:129]
	global_load_dwordx4 v[0:3], v[0:1], off
	s_nop 0
	global_load_dwordx4 v[4:7], v[18:19], off nt
	v_mov_b32_e32 v226, 0
	v_mov_b32_e32 v218, 0
	s_and_saveexec_b64 s[28:29], s[0:1]
	s_cbranch_execz .LBB0_823
	global_load_ushort v218, v[18:19], off offset:-2
.LBB0_823:
	s_or_b64 exec, exec, s[28:29]
	s_and_saveexec_b64 s[28:29], s[10:11]
	s_cbranch_execz .LBB0_825
	global_load_short_d16_hi v226, v[18:19], off offset:16
.LBB0_825:
	s_or_b64 exec, exec, s[28:29]
	v_mov_b32_e32 v131, v129
	v_lshl_add_u64 v[12:13], v[16:17], 0, v[130:131]
	global_load_dwordx4 v[8:11], v[12:13], off nt
	v_mov_b32_e32 v227, 0
	v_mov_b32_e32 v219, 0
	s_and_saveexec_b64 s[28:29], s[0:1]
	s_cbranch_execz .LBB0_827
	global_load_ushort v219, v[12:13], off offset:-2
.LBB0_827:
	s_or_b64 exec, exec, s[28:29]
	s_and_saveexec_b64 s[28:29], s[10:11]
	s_cbranch_execz .LBB0_829
	global_load_short_d16_hi v227, v[12:13], off offset:16
.LBB0_829:
	s_or_b64 exec, exec, s[28:29]
	v_add_co_u32_e32 v12, vcc, 0x4000, v18
	v_mov_b32_e32 v228, 0
	s_nop 0
	v_addc_co_u32_e32 v13, vcc, 0, v19, vcc
	global_load_dwordx4 v[12:15], v[12:13], off nt
	v_mov_b32_e32 v220, 0
	s_and_saveexec_b64 s[28:29], s[0:1]
	s_cbranch_execz .LBB0_831
	v_add_co_u32_e32 v20, vcc, 0x3000, v18
	s_nop 1
	v_addc_co_u32_e32 v21, vcc, 0, v19, vcc
	global_load_ushort v220, v[20:21], off offset:4094
.LBB0_831:
	s_or_b64 exec, exec, s[28:29]
	s_and_saveexec_b64 s[28:29], s[10:11]
	s_cbranch_execz .LBB0_833
	v_add_co_u32_e32 v18, vcc, 0x4000, v18
	s_nop 1
	v_addc_co_u32_e32 v19, vcc, 0, v19, vcc
	global_load_short_d16_hi v228, v[18:19], off offset:16
.LBB0_833:
	s_or_b64 exec, exec, s[28:29]
	v_mov_b32_e32 v133, v129
	v_lshl_add_u64 v[20:21], v[16:17], 0, v[132:133]
	global_load_dwordx4 v[16:19], v[20:21], off nt
	v_mov_b32_e32 v229, 0
	v_mov_b32_e32 v221, 0
	s_and_saveexec_b64 s[28:29], s[0:1]
	s_cbranch_execz .LBB0_835
	global_load_ushort v221, v[20:21], off offset:-2
.LBB0_835:
	s_or_b64 exec, exec, s[28:29]
	s_and_saveexec_b64 s[28:29], s[10:11]
	s_cbranch_execz .LBB0_837
	global_load_short_d16_hi v229, v[20:21], off offset:16
.LBB0_837:
	s_or_b64 exec, exec, s[28:29]
	s_ashr_i32 s35, s34, 31
	s_lshl_b64 s[12:13], s[34:35], 15
	v_lshl_add_u64 v[20:21], v[136:137], 0, s[12:13]
	v_lshl_add_u64 v[32:33], v[20:21], 0, s[18:19]
	v_lshl_add_u64 v[34:35], v[32:33], 0, v[128:129]
	global_load_dwordx4 v[20:23], v[34:35], off nt
	v_mov_b32_e32 v230, 0
	v_mov_b32_e32 v222, 0
	s_and_saveexec_b64 s[28:29], s[0:1]
	s_cbranch_execz .LBB0_839
	global_load_ushort v222, v[34:35], off offset:-2
.LBB0_839:
	s_or_b64 exec, exec, s[28:29]
	s_and_saveexec_b64 s[28:29], s[10:11]
	s_cbranch_execz .LBB0_841
	global_load_short_d16_hi v230, v[34:35], off offset:16
.LBB0_841:
	s_or_b64 exec, exec, s[28:29]
	v_mov_b32_e32 v131, v129
	v_lshl_add_u64 v[28:29], v[32:33], 0, v[130:131]
	global_load_dwordx4 v[24:27], v[28:29], off nt
	v_mov_b32_e32 v231, 0
	v_mov_b32_e32 v223, 0
	s_and_saveexec_b64 s[28:29], s[0:1]
	s_cbranch_execz .LBB0_843
	global_load_ushort v223, v[28:29], off offset:-2
.LBB0_843:
	s_or_b64 exec, exec, s[28:29]
	s_and_saveexec_b64 s[28:29], s[10:11]
	s_cbranch_execz .LBB0_845
	global_load_short_d16_hi v231, v[28:29], off offset:16
.LBB0_845:
	s_or_b64 exec, exec, s[28:29]
	v_add_co_u32_e32 v28, vcc, 0x4000, v34
	v_mov_b32_e32 v232, 0
	s_nop 0
	v_addc_co_u32_e32 v29, vcc, 0, v35, vcc
	global_load_dwordx4 v[28:31], v[28:29], off nt
	v_mov_b32_e32 v224, 0
	s_and_saveexec_b64 s[28:29], s[0:1]
	s_cbranch_execz .LBB0_847
	v_add_co_u32_e32 v36, vcc, 0x3000, v34
	s_nop 1
	v_addc_co_u32_e32 v37, vcc, 0, v35, vcc
	global_load_ushort v224, v[36:37], off offset:4094
.LBB0_847:
	s_or_b64 exec, exec, s[28:29]
	s_and_saveexec_b64 s[28:29], s[10:11]
	s_cbranch_execz .LBB0_849
	v_add_co_u32_e32 v34, vcc, 0x4000, v34
	s_nop 1
	v_addc_co_u32_e32 v35, vcc, 0, v35, vcc
	global_load_short_d16_hi v232, v[34:35], off offset:16
.LBB0_849:
	s_or_b64 exec, exec, s[28:29]
	v_mov_b32_e32 v133, v129
	v_lshl_add_u64 v[36:37], v[32:33], 0, v[132:133]
	global_load_dwordx4 v[32:35], v[36:37], off nt
	v_mov_b32_e32 v233, 0
	v_mov_b32_e32 v225, 0
	s_and_saveexec_b64 s[28:29], s[0:1]
	s_cbranch_execz .LBB0_851
	global_load_ushort v225, v[36:37], off offset:-2
.LBB0_851:
	s_or_b64 exec, exec, s[28:29]
	s_and_saveexec_b64 s[28:29], s[10:11]
	s_cbranch_execz .LBB0_853
	global_load_short_d16_hi v233, v[36:37], off offset:16
.LBB0_853:
	s_or_b64 exec, exec, s[28:29]
.LBB0_854:
	ds_read_b128 v[40:43], v188
	ds_read_b128 v[44:47], v188 offset:32
	ds_read_b128 v[68:71], v188 offset:64
	ds_read_b128 v[48:51], v188 offset:96
	ds_read_b128 v[76:79], v188 offset:128
	ds_read_b128 v[52:55], v188 offset:160
	ds_read_b128 v[92:95], v188 offset:192
	ds_read_b128 v[56:59], v188 offset:224
	ds_read_b128 v[64:67], v198
	v_mov_b32_e32 v100, 0
	s_mov_b32 s2, 0
	s_mov_b32 s12, 3
	v_mov_b32_e32 v108, v135
	s_mov_b32 s13, 0
	v_mov_b32_e32 v101, v100
	v_mov_b32_e32 v102, v100
	v_mov_b32_e32 v103, v100
	v_mov_b32_e32 v96, v100
	v_mov_b32_e32 v97, v100
	v_mov_b32_e32 v98, v100
	v_mov_b32_e32 v99, v100
	v_mov_b32_e32 v88, v100
	v_mov_b32_e32 v89, v100
	v_mov_b32_e32 v90, v100
	v_mov_b32_e32 v91, v100
	v_mov_b32_e32 v84, v100
	v_mov_b32_e32 v85, v100
	v_mov_b32_e32 v86, v100
	v_mov_b32_e32 v87, v100
	v_mov_b32_e32 v80, v100
	v_mov_b32_e32 v81, v100
	v_mov_b32_e32 v82, v100
	v_mov_b32_e32 v83, v100
	v_mov_b32_e32 v72, v100
	v_mov_b32_e32 v73, v100
	v_mov_b32_e32 v74, v100
	v_mov_b32_e32 v75, v100
	v_mov_b32_e32 v60, v100
	v_mov_b32_e32 v61, v100
	v_mov_b32_e32 v62, v100
	v_mov_b32_e32 v63, v100
	v_mov_b32_e32 v36, v100
	v_mov_b32_e32 v37, v100
	v_mov_b32_e32 v38, v100
	v_mov_b32_e32 v39, v100
	s_branch .LBB0_856

.LBB0_1074:
	ds_read_b128 v[128:131], v165
	ds_read_b128 v[132:135], v165 offset:1024
	ds_read_b128 v[136:139], v165 offset:2048
	ds_read_b128 v[140:143], v165 offset:3072
	s_add_u32 s44, s42, 0xfff80080
	s_addc_u32 s45, s43, -1
	s_cmp_eq_u32 s70, 28
	s_cselect_b32 s47, s31, s45
	s_cselect_b32 s46, s68, s44
	s_cselect_b32 s45, s19, s69
	s_cselect_b32 s44, s28, s29
	v_lshl_add_u64 v[160:161], s[42:43], 0, v[150:151]
	s_add_i32 m0, s41, 0xc000
	ds_read_b128 v[156:159], v166
	ds_read_b128 v[168:171], v166 offset:1024
	ds_read_b128 v[172:175], v166 offset:2048
	ds_read_b128 v[176:179], v166 offset:3072
	ds_read_b128 v[180:183], v166 offset:4096
	ds_read_b128 v[184:187], v166 offset:5120
	ds_read_b128 v[188:191], v166 offset:6144
	ds_read_b128 v[192:195], v166 offset:7168
	global_load_lds_dwordx4 v[160:161], off
	v_lshl_add_u64 v[160:161], s[42:43], 0, v[152:153]
	s_add_i32 m0, s41, 0xe000
	s_nop 0
	global_load_lds_dwordx4 v[160:161], off
	s_waitcnt lgkmcnt(8)
	s_barrier
	s_waitcnt lgkmcnt(0)
	s_setprio 1
	s_waitcnt lgkmcnt(0)
	v_mfma_f32_16x16x32_bf16 v[124:127], v[128:131], v[156:159], v[124:127]
	v_mfma_f32_16x16x32_bf16 v[120:123], v[136:139], v[156:159], v[120:123]
	v_mfma_f32_16x16x32_bf16 v[112:115], v[128:131], v[172:175], v[112:115]
	v_mfma_f32_16x16x32_bf16 v[104:107], v[136:139], v[172:175], v[104:107]
	v_mfma_f32_16x16x32_bf16 v[96:99], v[128:131], v[180:183], v[96:99]
	v_mfma_f32_16x16x32_bf16 v[88:91], v[136:139], v[180:183], v[88:91]
	v_mfma_f32_16x16x32_bf16 v[80:83], v[128:131], v[188:191], v[80:83]
	v_mfma_f32_16x16x32_bf16 v[72:75], v[136:139], v[188:191], v[72:75]
	v_mfma_f32_16x16x32_bf16 v[124:127], v[132:135], v[168:171], v[124:127]
	v_mfma_f32_16x16x32_bf16 v[120:123], v[140:143], v[168:171], v[120:123]
	v_mfma_f32_16x16x32_bf16 v[112:115], v[132:135], v[176:179], v[112:115]
	v_mfma_f32_16x16x32_bf16 v[104:107], v[140:143], v[176:179], v[104:107]
	v_mfma_f32_16x16x32_bf16 v[96:99], v[132:135], v[184:187], v[96:99]
	v_mfma_f32_16x16x32_bf16 v[88:91], v[140:143], v[184:187], v[88:91]
	v_mfma_f32_16x16x32_bf16 v[80:83], v[132:135], v[192:195], v[80:83]
	v_mfma_f32_16x16x32_bf16 v[72:75], v[140:143], v[192:195], v[72:75]
	s_setprio 0
	s_barrier
	s_add_i32 s71, s65, s54
	v_lshl_add_u64 v[160:161], s[44:45], 0, v[146:147]
	s_mov_b32 m0, s71
	ds_read_b128 v[196:199], v167
	ds_read_b128 v[200:203], v167 offset:1024
	ds_read_b128 v[204:207], v167 offset:2048
	ds_read_b128 v[208:211], v167 offset:3072
	global_load_lds_dwordx4 v[160:161], off
	v_lshl_add_u64 v[212:213], s[44:45], 0, v[148:149]
	s_add_i32 m0, s71, 0x2000
	s_nop 0
	global_load_lds_dwordx4 v[212:213], off
	s_barrier
	s_waitcnt lgkmcnt(0)
	s_setprio 1
	s_waitcnt lgkmcnt(0)
	v_mfma_f32_16x16x32_bf16 v[116:119], v[196:199], v[156:159], v[116:119]
	v_mfma_f32_16x16x32_bf16 v[108:111], v[204:207], v[156:159], v[108:111]
	v_mfma_f32_16x16x32_bf16 v[100:103], v[196:199], v[172:175], v[100:103]
	v_mfma_f32_16x16x32_bf16 v[92:95], v[204:207], v[172:175], v[92:95]
	v_mfma_f32_16x16x32_bf16 v[84:87], v[196:199], v[180:183], v[84:87]
	v_mfma_f32_16x16x32_bf16 v[76:79], v[204:207], v[180:183], v[76:79]
	v_mfma_f32_16x16x32_bf16 v[68:71], v[196:199], v[188:191], v[68:71]
	v_mfma_f32_16x16x32_bf16 v[64:67], v[204:207], v[188:191], v[64:67]
	v_mfma_f32_16x16x32_bf16 v[116:119], v[200:203], v[168:171], v[116:119]
	v_mfma_f32_16x16x32_bf16 v[108:111], v[208:211], v[168:171], v[108:111]
	v_mfma_f32_16x16x32_bf16 v[100:103], v[200:203], v[176:179], v[100:103]
	v_mfma_f32_16x16x32_bf16 v[92:95], v[208:211], v[176:179], v[92:95]
	v_mfma_f32_16x16x32_bf16 v[84:87], v[200:203], v[184:187], v[84:87]
	v_mfma_f32_16x16x32_bf16 v[76:79], v[208:211], v[184:187], v[76:79]
	v_mfma_f32_16x16x32_bf16 v[68:71], v[200:203], v[192:195], v[68:71]
	v_mfma_f32_16x16x32_bf16 v[64:67], v[208:211], v[192:195], v[64:67]
	s_setprio 0
	s_mov_b32 m0, s41
	v_lshl_add_u64 v[214:215], s[46:47], 0, v[146:147]
	s_barrier
	ds_read_b128 v[156:159], v166 offset:16384
	ds_read_b128 v[168:171], v166 offset:17408
	ds_read_b128 v[172:175], v166 offset:18432
	ds_read_b128 v[176:179], v166 offset:19456
	ds_read_b128 v[180:183], v166 offset:20480
	ds_read_b128 v[184:187], v166 offset:21504
	ds_read_b128 v[188:191], v166 offset:22528
	ds_read_b128 v[192:195], v166 offset:23552
	global_load_lds_dwordx4 v[214:215], off
	v_lshl_add_u64 v[216:217], s[46:47], 0, v[148:149]
	s_mov_b32 m0, s55
	s_nop 0
	global_load_lds_dwordx4 v[216:217], off
	s_barrier
	s_waitcnt lgkmcnt(0)
	s_setprio 1
	s_waitcnt lgkmcnt(0)
	v_mfma_f32_16x16x32_bf16 v[60:63], v[128:131], v[156:159], v[60:63]
	v_mfma_f32_16x16x32_bf16 v[56:59], v[136:139], v[156:159], v[56:59]
	v_mfma_f32_16x16x32_bf16 v[48:51], v[128:131], v[172:175], v[48:51]
	v_mfma_f32_16x16x32_bf16 v[40:43], v[136:139], v[172:175], v[40:43]
	v_mfma_f32_16x16x32_bf16 v[32:35], v[128:131], v[180:183], v[32:35]
	v_mfma_f32_16x16x32_bf16 v[24:27], v[136:139], v[180:183], v[24:27]
	v_mfma_f32_16x16x32_bf16 v[16:19], v[128:131], v[188:191], v[16:19]
	v_mfma_f32_16x16x32_bf16 v[8:11], v[136:139], v[188:191], v[8:11]
	v_mfma_f32_16x16x32_bf16 v[60:63], v[132:135], v[168:171], v[60:63]
	v_mfma_f32_16x16x32_bf16 v[56:59], v[140:143], v[168:171], v[56:59]
	v_mfma_f32_16x16x32_bf16 v[48:51], v[132:135], v[176:179], v[48:51]
	v_mfma_f32_16x16x32_bf16 v[40:43], v[140:143], v[176:179], v[40:43]
	v_mfma_f32_16x16x32_bf16 v[32:35], v[132:135], v[184:187], v[32:35]
	v_mfma_f32_16x16x32_bf16 v[24:27], v[140:143], v[184:187], v[24:27]
	v_mfma_f32_16x16x32_bf16 v[16:19], v[132:135], v[192:195], v[16:19]
	v_mfma_f32_16x16x32_bf16 v[8:11], v[140:143], v[192:195], v[8:11]
	s_setprio 0
	s_barrier
	s_add_u32 s72, s44, 0x80000
	s_addc_u32 s73, s45, 0
	s_add_i32 s71, s66, s54
	v_lshl_add_u64 v[128:129], s[72:73], 0, v[146:147]
	s_mov_b32 m0, s71
	s_nop 0
	global_load_lds_dwordx4 v[128:129], off
	v_lshl_add_u64 v[128:129], s[72:73], 0, v[148:149]
	s_add_i32 m0, s71, 0x2000
	s_nop 0
	global_load_lds_dwordx4 v[128:129], off
	s_waitcnt vmcnt(6)
	s_barrier
	s_setprio 1
	v_mfma_f32_16x16x32_bf16 v[52:55], v[196:199], v[156:159], v[52:55]
	v_mfma_f32_16x16x32_bf16 v[44:47], v[204:207], v[156:159], v[44:47]
	v_mfma_f32_16x16x32_bf16 v[36:39], v[196:199], v[172:175], v[36:39]
	v_mfma_f32_16x16x32_bf16 v[28:31], v[204:207], v[172:175], v[28:31]
	v_mfma_f32_16x16x32_bf16 v[20:23], v[196:199], v[180:183], v[20:23]
	v_mfma_f32_16x16x32_bf16 v[12:15], v[204:207], v[180:183], v[12:15]
	v_mfma_f32_16x16x32_bf16 v[4:7], v[196:199], v[188:191], v[4:7]
	v_mfma_f32_16x16x32_bf16 v[0:3], v[204:207], v[188:191], v[0:3]
	v_mfma_f32_16x16x32_bf16 v[52:55], v[200:203], v[168:171], v[52:55]
	v_mfma_f32_16x16x32_bf16 v[44:47], v[208:211], v[168:171], v[44:47]
	v_mfma_f32_16x16x32_bf16 v[36:39], v[200:203], v[176:179], v[36:39]
	v_mfma_f32_16x16x32_bf16 v[28:31], v[208:211], v[176:179], v[28:31]
	v_mfma_f32_16x16x32_bf16 v[20:23], v[200:203], v[184:187], v[20:23]
	v_mfma_f32_16x16x32_bf16 v[12:15], v[208:211], v[184:187], v[12:15]
	v_mfma_f32_16x16x32_bf16 v[4:7], v[200:203], v[192:195], v[4:7]
	v_mfma_f32_16x16x32_bf16 v[0:3], v[208:211], v[192:195], v[0:3]
	s_setprio 0
	s_add_i32 s71, 0, 0x18000
	v_add_u32_e32 v140, s71, v163
	s_barrier
	ds_read_b128 v[128:131], v140
	ds_read_b128 v[132:135], v140 offset:1024
	ds_read_b128 v[136:139], v140 offset:2048
	ds_read_b128 v[140:143], v140 offset:3072
	s_add_u32 s46, s46, 0x80000
	s_addc_u32 s47, s47, 0
	s_mov_b32 m0, s56
	v_lshl_add_u64 v[196:197], s[46:47], 0, v[146:147]
	ds_read_b128 v[156:159], v166 offset:32768
	ds_read_b128 v[168:171], v166 offset:33792
	ds_read_b128 v[172:175], v166 offset:34816
	ds_read_b128 v[176:179], v166 offset:35840
	ds_read_b128 v[180:183], v166 offset:36864
	ds_read_b128 v[184:187], v166 offset:37888
	ds_read_b128 v[188:191], v166 offset:38912
	ds_read_b128 v[192:195], v166 offset:39936
	global_load_lds_dwordx4 v[196:197], off
	v_lshl_add_u64 v[196:197], s[46:47], 0, v[148:149]
	s_mov_b32 m0, s57
	s_nop 0
	global_load_lds_dwordx4 v[196:197], off
	s_waitcnt lgkmcnt(8)
	s_barrier
	s_waitcnt lgkmcnt(0)
	s_setprio 1
	s_waitcnt lgkmcnt(0)
	v_mfma_f32_16x16x32_bf16 v[124:127], v[128:131], v[156:159], v[124:127]
	v_mfma_f32_16x16x32_bf16 v[120:123], v[136:139], v[156:159], v[120:123]
	v_mfma_f32_16x16x32_bf16 v[112:115], v[128:131], v[172:175], v[112:115]
	v_mfma_f32_16x16x32_bf16 v[104:107], v[136:139], v[172:175], v[104:107]
	v_mfma_f32_16x16x32_bf16 v[96:99], v[128:131], v[180:183], v[96:99]
	v_mfma_f32_16x16x32_bf16 v[88:91], v[136:139], v[180:183], v[88:91]
	v_mfma_f32_16x16x32_bf16 v[80:83], v[128:131], v[188:191], v[80:83]
	v_mfma_f32_16x16x32_bf16 v[72:75], v[136:139], v[188:191], v[72:75]
	v_mfma_f32_16x16x32_bf16 v[124:127], v[132:135], v[168:171], v[124:127]
	v_mfma_f32_16x16x32_bf16 v[120:123], v[140:143], v[168:171], v[120:123]
	v_mfma_f32_16x16x32_bf16 v[112:115], v[132:135], v[176:179], v[112:115]
	v_mfma_f32_16x16x32_bf16 v[104:107], v[140:143], v[176:179], v[104:107]
	v_mfma_f32_16x16x32_bf16 v[96:99], v[132:135], v[184:187], v[96:99]
	v_mfma_f32_16x16x32_bf16 v[88:91], v[140:143], v[184:187], v[88:91]
	v_mfma_f32_16x16x32_bf16 v[80:83], v[132:135], v[192:195], v[80:83]
	v_mfma_f32_16x16x32_bf16 v[72:75], v[140:143], v[192:195], v[72:75]
	s_setprio 0
	s_barrier
	s_add_i32 s46, 0, 0x1c000
	s_add_i32 s47, s71, s54
	v_add_u32_e32 v208, s46, v163
	v_lshl_add_u64 v[160:161], v[160:161], 0, s[8:9]
	s_mov_b32 m0, s47
	ds_read_b128 v[196:199], v208
	ds_read_b128 v[200:203], v208 offset:1024
	ds_read_b128 v[204:207], v208 offset:2048
	ds_read_b128 v[208:211], v208 offset:3072
	global_load_lds_dwordx4 v[160:161], off
	v_lshl_add_u64 v[160:161], v[212:213], 0, s[8:9]
	s_add_i32 m0, s47, 0x2000
	s_nop 0
	global_load_lds_dwordx4 v[160:161], off
	s_barrier
	s_waitcnt lgkmcnt(0)
	s_setprio 1
	s_waitcnt lgkmcnt(0)
	v_mfma_f32_16x16x32_bf16 v[116:119], v[196:199], v[156:159], v[116:119]
	v_mfma_f32_16x16x32_bf16 v[108:111], v[204:207], v[156:159], v[108:111]
	v_mfma_f32_16x16x32_bf16 v[100:103], v[196:199], v[172:175], v[100:103]
	v_mfma_f32_16x16x32_bf16 v[92:95], v[204:207], v[172:175], v[92:95]
	v_mfma_f32_16x16x32_bf16 v[84:87], v[196:199], v[180:183], v[84:87]
	v_mfma_f32_16x16x32_bf16 v[76:79], v[204:207], v[180:183], v[76:79]
	v_mfma_f32_16x16x32_bf16 v[68:71], v[196:199], v[188:191], v[68:71]
	v_mfma_f32_16x16x32_bf16 v[64:67], v[204:207], v[188:191], v[64:67]
	v_mfma_f32_16x16x32_bf16 v[116:119], v[200:203], v[168:171], v[116:119]
	v_mfma_f32_16x16x32_bf16 v[108:111], v[208:211], v[168:171], v[108:111]
	v_mfma_f32_16x16x32_bf16 v[100:103], v[200:203], v[176:179], v[100:103]
	v_mfma_f32_16x16x32_bf16 v[92:95], v[208:211], v[176:179], v[92:95]
	v_mfma_f32_16x16x32_bf16 v[84:87], v[200:203], v[184:187], v[84:87]
	v_mfma_f32_16x16x32_bf16 v[76:79], v[208:211], v[184:187], v[76:79]
	v_mfma_f32_16x16x32_bf16 v[68:71], v[200:203], v[192:195], v[68:71]
	v_mfma_f32_16x16x32_bf16 v[64:67], v[208:211], v[192:195], v[64:67]
	s_setprio 0
	s_mov_b32 m0, s61
	v_lshl_add_u64 v[160:161], v[214:215], 0, s[8:9]
	s_barrier
	ds_read_b128 v[156:159], v166 offset:49152
	ds_read_b128 v[168:171], v166 offset:50176
	ds_read_b128 v[172:175], v166 offset:51200
	ds_read_b128 v[176:179], v166 offset:52224
	ds_read_b128 v[180:183], v166 offset:53248
	ds_read_b128 v[184:187], v166 offset:54272
	ds_read_b128 v[188:191], v166 offset:55296
	ds_read_b128 v[192:195], v166 offset:56320
	global_load_lds_dwordx4 v[160:161], off
	v_lshl_add_u64 v[160:161], v[216:217], 0, s[8:9]
	s_mov_b32 m0, s62
	s_nop 0
	global_load_lds_dwordx4 v[160:161], off
	s_barrier
	s_waitcnt lgkmcnt(0)
	s_setprio 1
	s_waitcnt lgkmcnt(0)
	v_mfma_f32_16x16x32_bf16 v[60:63], v[128:131], v[156:159], v[60:63]
	v_mfma_f32_16x16x32_bf16 v[56:59], v[136:139], v[156:159], v[56:59]
	v_mfma_f32_16x16x32_bf16 v[48:51], v[128:131], v[172:175], v[48:51]
	v_mfma_f32_16x16x32_bf16 v[40:43], v[136:139], v[172:175], v[40:43]
	v_mfma_f32_16x16x32_bf16 v[32:35], v[128:131], v[180:183], v[32:35]
	v_mfma_f32_16x16x32_bf16 v[24:27], v[136:139], v[180:183], v[24:27]
	v_mfma_f32_16x16x32_bf16 v[16:19], v[128:131], v[188:191], v[16:19]
	v_mfma_f32_16x16x32_bf16 v[8:11], v[136:139], v[188:191], v[8:11]
	v_mfma_f32_16x16x32_bf16 v[60:63], v[132:135], v[168:171], v[60:63]
	v_mfma_f32_16x16x32_bf16 v[56:59], v[140:143], v[168:171], v[56:59]
	v_mfma_f32_16x16x32_bf16 v[48:51], v[132:135], v[176:179], v[48:51]
	v_mfma_f32_16x16x32_bf16 v[40:43], v[140:143], v[176:179], v[40:43]
	v_mfma_f32_16x16x32_bf16 v[32:35], v[132:135], v[184:187], v[32:35]
	v_mfma_f32_16x16x32_bf16 v[24:27], v[140:143], v[184:187], v[24:27]
	v_mfma_f32_16x16x32_bf16 v[16:19], v[132:135], v[192:195], v[16:19]
	v_mfma_f32_16x16x32_bf16 v[8:11], v[140:143], v[192:195], v[8:11]
	s_setprio 0
	s_barrier
	s_add_u32 s44, s44, 0x80080
	s_addc_u32 s45, s45, 0
	s_add_i32 s46, s46, s54
	v_lshl_add_u64 v[128:129], s[44:45], 0, v[146:147]
	s_mov_b32 m0, s46
	s_nop 0
	global_load_lds_dwordx4 v[128:129], off
	v_lshl_add_u64 v[128:129], s[44:45], 0, v[148:149]
	s_add_i32 m0, s46, 0x2000
	s_nop 0
	global_load_lds_dwordx4 v[128:129], off
	s_waitcnt vmcnt(6)
	s_barrier
	s_setprio 1
	v_mfma_f32_16x16x32_bf16 v[52:55], v[196:199], v[156:159], v[52:55]
	v_mfma_f32_16x16x32_bf16 v[44:47], v[204:207], v[156:159], v[44:47]
	v_mfma_f32_16x16x32_bf16 v[36:39], v[196:199], v[172:175], v[36:39]
	v_mfma_f32_16x16x32_bf16 v[28:31], v[204:207], v[172:175], v[28:31]
	v_mfma_f32_16x16x32_bf16 v[20:23], v[196:199], v[180:183], v[20:23]
	v_mfma_f32_16x16x32_bf16 v[12:15], v[204:207], v[180:183], v[12:15]
	v_mfma_f32_16x16x32_bf16 v[4:7], v[196:199], v[188:191], v[4:7]
	v_mfma_f32_16x16x32_bf16 v[0:3], v[204:207], v[188:191], v[0:3]
	v_mfma_f32_16x16x32_bf16 v[52:55], v[200:203], v[168:171], v[52:55]
	v_mfma_f32_16x16x32_bf16 v[44:47], v[208:211], v[168:171], v[44:47]
	v_mfma_f32_16x16x32_bf16 v[36:39], v[200:203], v[176:179], v[36:39]
	v_mfma_f32_16x16x32_bf16 v[28:31], v[208:211], v[176:179], v[28:31]
	v_mfma_f32_16x16x32_bf16 v[20:23], v[200:203], v[184:187], v[20:23]
	v_mfma_f32_16x16x32_bf16 v[12:15], v[208:211], v[184:187], v[12:15]
	v_mfma_f32_16x16x32_bf16 v[4:7], v[200:203], v[192:195], v[4:7]
	v_mfma_f32_16x16x32_bf16 v[0:3], v[208:211], v[192:195], v[0:3]
	s_setprio 0
	s_add_i32 s70, s70, 2
	s_add_u32 s42, s42, 0x100
	s_addc_u32 s43, s43, 0
	s_add_u32 s29, s29, 0x100
	s_addc_u32 s69, s69, 0
	s_cmp_gt_u32 s70, 29
	s_barrier
	s_cbranch_scc0 .LBB0_1074
	s_ashr_i32 s19, s40, 3
	v_lshl_add_u32 v160, s40, 8, v162
	v_lshl_or_b32 v158, s67, 8, v164
	s_mul_hi_i32 s29, s19, 0xc000
	s_mul_i32 s19, s19, 0xc000
	v_ashrrev_i32_e32 v161, 31, v160
	s_add_u32 s28, s59, s19
	v_ashrrev_i32_e32 v159, 31, v158
	v_lshlrev_b64 v[130:131], 11, v[160:161]
	s_addc_u32 s29, s60, s29
	v_lshl_add_u64 v[156:157], v[130:131], 0, v[158:159]
	v_lshl_add_u64 v[128:129], v[158:159], 2, s[28:29]
	v_lshl_add_u64 v[172:173], v[156:157], 2, s[52:53]
	global_load_dwordx4 v[136:139], v[128:129], off
	v_lshlrev_b64 v[174:175], 1, v[156:157]
	v_lshl_add_u64 v[176:177], s[6:7], 0, v[174:175]
	global_load_dwordx4 v[140:143], v[128:129], off offset:64
	global_load_dwordx4 v[132:135], v[128:129], off offset:512
	s_nop 0
	global_load_dwordx4 v[128:131], v[128:129], off offset:576
	s_mov_b32 s67, s18
	s_mov_b32 s40, s30
	s_mov_b64 s[44:45], s[38:39]
	s_mov_b64 s[42:43], s[36:37]
	s_mov_b32 s29, 0
	global_load_dwordx4 v[180:183], v[172:173], off
	global_load_dwordx4 v[184:187], v[172:173], off offset:64
	global_load_dwordx4 v[188:191], v[172:173], off offset:512
	global_load_dwordx4 v[192:195], v[172:173], off offset:576
	s_mov_b32 s28, 0x20000
	v_lshl_add_u64 v[168:169], v[172:173], 0, s[28:29]
	global_load_dwordx4 v[196:199], v[168:169], off
	global_load_dwordx4 v[200:203], v[168:169], off offset:64
	global_load_dwordx4 v[204:207], v[168:169], off offset:512
	global_load_dwordx4 v[208:211], v[168:169], off offset:576
	s_mov_b32 s28, 0x40000
	v_lshl_add_u64 v[168:169], v[172:173], 0, s[28:29]
	global_load_dwordx4 v[212:215], v[168:169], off
	global_load_dwordx4 v[216:219], v[168:169], off offset:64
	global_load_dwordx4 v[220:223], v[168:169], off offset:512
	global_load_dwordx4 v[224:227], v[168:169], off offset:576
	s_mov_b32 s28, 0x60000
	v_lshl_add_u64 v[168:169], v[172:173], 0, s[28:29]
	global_load_dwordx4 v[228:231], v[168:169], off
	global_load_dwordx4 v[232:235], v[168:169], off offset:64
	global_load_dwordx4 v[236:239], v[168:169], off offset:512
	global_load_dwordx4 v[240:243], v[168:169], off offset:576
	s_mov_b32 s28, 0x100000
	v_lshl_add_u64 v[168:169], v[172:173], 0, s[28:29]
	s_waitcnt vmcnt(15)
	v_pk_fma_f32 v[124:125], v[124:125], v[136:137], v[180:181]
	v_pk_fma_f32 v[126:127], v[126:127], v[138:139], v[182:183]
	v_cvt_pk_bf16_f32 v124, v124, v125
	v_cvt_pk_bf16_f32 v125, v126, v127
	global_store_dwordx2 v[176:177], v[124:125], off
	global_load_dwordx4 v[180:183], v[168:169], off
	s_waitcnt vmcnt(16)
	v_pk_fma_f32 v[120:121], v[120:121], v[140:141], v[184:185]
	v_pk_fma_f32 v[122:123], v[122:123], v[142:143], v[186:187]
	v_cvt_pk_bf16_f32 v120, v120, v121
	v_cvt_pk_bf16_f32 v121, v122, v123
	global_store_dwordx2 v[176:177], v[120:121], off offset:32
	global_load_dwordx4 v[184:187], v[168:169], off offset:64
	s_waitcnt vmcnt(17)
	v_pk_fma_f32 v[116:117], v[116:117], v[132:133], v[188:189]
	v_pk_fma_f32 v[118:119], v[118:119], v[134:135], v[190:191]
	v_cvt_pk_bf16_f32 v116, v116, v117
	v_cvt_pk_bf16_f32 v117, v118, v119
	global_store_dwordx2 v[176:177], v[116:117], off offset:256
	global_load_dwordx4 v[188:191], v[168:169], off offset:512
	s_waitcnt vmcnt(18)
	v_pk_fma_f32 v[108:109], v[108:109], v[128:129], v[192:193]
	v_pk_fma_f32 v[110:111], v[110:111], v[130:131], v[194:195]
	v_cvt_pk_bf16_f32 v108, v108, v109
	v_cvt_pk_bf16_f32 v109, v110, v111
	global_store_dwordx2 v[176:177], v[108:109], off offset:288
	global_load_dwordx4 v[192:195], v[168:169], off offset:576
	s_mov_b32 s28, 0x10000
	v_lshl_add_u64 v[170:171], v[176:177], 0, s[28:29]
	s_mov_b32 s28, 0x120000
	v_lshl_add_u64 v[168:169], v[172:173], 0, s[28:29]
	s_waitcnt vmcnt(19)
	v_pk_fma_f32 v[112:113], v[112:113], v[136:137], v[196:197]
	v_pk_fma_f32 v[114:115], v[114:115], v[138:139], v[198:199]
	v_cvt_pk_bf16_f32 v112, v112, v113
	v_cvt_pk_bf16_f32 v113, v114, v115
	global_store_dwordx2 v[170:171], v[112:113], off
	global_load_dwordx4 v[196:199], v[168:169], off
	s_waitcnt vmcnt(20)
	v_pk_fma_f32 v[104:105], v[104:105], v[140:141], v[200:201]
	v_pk_fma_f32 v[106:107], v[106:107], v[142:143], v[202:203]
	v_cvt_pk_bf16_f32 v104, v104, v105
	v_cvt_pk_bf16_f32 v105, v106, v107
	global_store_dwordx2 v[170:171], v[104:105], off offset:32
	global_load_dwordx4 v[200:203], v[168:169], off offset:64
	s_waitcnt vmcnt(21)
	v_pk_fma_f32 v[100:101], v[100:101], v[132:133], v[204:205]
	v_pk_fma_f32 v[102:103], v[102:103], v[134:135], v[206:207]
	v_cvt_pk_bf16_f32 v100, v100, v101
	v_cvt_pk_bf16_f32 v101, v102, v103
	global_store_dwordx2 v[170:171], v[100:101], off offset:256
	global_load_dwordx4 v[204:207], v[168:169], off offset:512
	s_waitcnt vmcnt(22)
	v_pk_fma_f32 v[92:93], v[92:93], v[128:129], v[208:209]
	v_pk_fma_f32 v[94:95], v[94:95], v[130:131], v[210:211]
	v_cvt_pk_bf16_f32 v92, v92, v93
	v_cvt_pk_bf16_f32 v93, v94, v95
	global_store_dwordx2 v[170:171], v[92:93], off offset:288
	global_load_dwordx4 v[208:211], v[168:169], off offset:576
	s_mov_b32 s28, 0x20000
	v_lshl_add_u64 v[170:171], v[176:177], 0, s[28:29]
	s_mov_b32 s28, 0x140000
	v_lshl_add_u64 v[168:169], v[172:173], 0, s[28:29]
	s_waitcnt vmcnt(23)
	v_pk_fma_f32 v[96:97], v[96:97], v[136:137], v[212:213]
	v_pk_fma_f32 v[98:99], v[98:99], v[138:139], v[214:215]
	v_cvt_pk_bf16_f32 v96, v96, v97
	v_cvt_pk_bf16_f32 v97, v98, v99
	global_store_dwordx2 v[170:171], v[96:97], off
	global_load_dwordx4 v[212:215], v[168:169], off
	s_waitcnt vmcnt(24)
	v_pk_fma_f32 v[88:89], v[88:89], v[140:141], v[216:217]
	v_pk_fma_f32 v[90:91], v[90:91], v[142:143], v[218:219]
	v_cvt_pk_bf16_f32 v88, v88, v89
	v_cvt_pk_bf16_f32 v89, v90, v91
	global_store_dwordx2 v[170:171], v[88:89], off offset:32
	global_load_dwordx4 v[216:219], v[168:169], off offset:64
	s_waitcnt vmcnt(25)
	v_pk_fma_f32 v[84:85], v[84:85], v[132:133], v[220:221]
	v_pk_fma_f32 v[86:87], v[86:87], v[134:135], v[222:223]
	v_cvt_pk_bf16_f32 v84, v84, v85
	v_cvt_pk_bf16_f32 v85, v86, v87
	global_store_dwordx2 v[170:171], v[84:85], off offset:256
	global_load_dwordx4 v[220:223], v[168:169], off offset:512
	s_waitcnt vmcnt(26)
	v_pk_fma_f32 v[76:77], v[76:77], v[128:129], v[224:225]
	v_pk_fma_f32 v[78:79], v[78:79], v[130:131], v[226:227]
	v_cvt_pk_bf16_f32 v76, v76, v77
	v_cvt_pk_bf16_f32 v77, v78, v79
	global_store_dwordx2 v[170:171], v[76:77], off offset:288
	global_load_dwordx4 v[224:227], v[168:169], off offset:576
	s_mov_b32 s28, 0x30000
	v_lshl_add_u64 v[170:171], v[176:177], 0, s[28:29]
	s_mov_b32 s28, 0x160000
	v_lshl_add_u64 v[168:169], v[172:173], 0, s[28:29]
	s_waitcnt vmcnt(27)
	v_pk_fma_f32 v[80:81], v[80:81], v[136:137], v[228:229]
	v_pk_fma_f32 v[82:83], v[82:83], v[138:139], v[230:231]
	v_cvt_pk_bf16_f32 v80, v80, v81
	v_cvt_pk_bf16_f32 v81, v82, v83
	global_store_dwordx2 v[170:171], v[80:81], off
	global_load_dwordx4 v[228:231], v[168:169], off
	s_waitcnt vmcnt(28)
	v_pk_fma_f32 v[72:73], v[72:73], v[140:141], v[232:233]
	v_pk_fma_f32 v[74:75], v[74:75], v[142:143], v[234:235]
	v_cvt_pk_bf16_f32 v72, v72, v73
	v_cvt_pk_bf16_f32 v73, v74, v75
	global_store_dwordx2 v[170:171], v[72:73], off offset:32
	global_load_dwordx4 v[232:235], v[168:169], off offset:64
	s_waitcnt vmcnt(29)
	v_pk_fma_f32 v[68:69], v[68:69], v[132:133], v[236:237]
	v_pk_fma_f32 v[70:71], v[70:71], v[134:135], v[238:239]
	v_cvt_pk_bf16_f32 v68, v68, v69
	v_cvt_pk_bf16_f32 v69, v70, v71
	global_store_dwordx2 v[170:171], v[68:69], off offset:256
	global_load_dwordx4 v[236:239], v[168:169], off offset:512
	s_waitcnt vmcnt(30)
	v_pk_fma_f32 v[64:65], v[64:65], v[128:129], v[240:241]
	v_pk_fma_f32 v[66:67], v[66:67], v[130:131], v[242:243]
	v_cvt_pk_bf16_f32 v64, v64, v65
	v_cvt_pk_bf16_f32 v65, v66, v67
	global_store_dwordx2 v[170:171], v[64:65], off offset:288
	global_load_dwordx4 v[240:243], v[168:169], off offset:576
	s_mov_b32 s28, 0x80000
	v_lshl_add_u64 v[170:171], v[176:177], 0, s[28:29]
	s_waitcnt vmcnt(30)
	v_pk_fma_f32 v[60:61], v[60:61], v[136:137], v[180:181]
	v_pk_fma_f32 v[62:63], v[62:63], v[138:139], v[182:183]
	v_cvt_pk_bf16_f32 v60, v60, v61
	v_cvt_pk_bf16_f32 v61, v62, v63
	global_store_dwordx2 v[170:171], v[60:61], off
	s_waitcnt vmcnt(29)
	v_pk_fma_f32 v[56:57], v[56:57], v[140:141], v[184:185]
	v_pk_fma_f32 v[58:59], v[58:59], v[142:143], v[186:187]
	v_cvt_pk_bf16_f32 v56, v56, v57
	v_cvt_pk_bf16_f32 v57, v58, v59
	global_store_dwordx2 v[170:171], v[56:57], off offset:32
	s_waitcnt vmcnt(28)
	v_pk_fma_f32 v[52:53], v[52:53], v[132:133], v[188:189]
	v_pk_fma_f32 v[54:55], v[54:55], v[134:135], v[190:191]
	v_cvt_pk_bf16_f32 v52, v52, v53
	v_cvt_pk_bf16_f32 v53, v54, v55
	global_store_dwordx2 v[170:171], v[52:53], off offset:256
	s_waitcnt vmcnt(27)
	v_pk_fma_f32 v[44:45], v[44:45], v[128:129], v[192:193]
	v_pk_fma_f32 v[46:47], v[46:47], v[130:131], v[194:195]
	v_cvt_pk_bf16_f32 v44, v44, v45
	v_cvt_pk_bf16_f32 v45, v46, v47
	global_store_dwordx2 v[170:171], v[44:45], off offset:288
	s_mov_b32 s28, 0x90000
	v_lshl_add_u64 v[170:171], v[176:177], 0, s[28:29]
	s_waitcnt vmcnt(26)
	v_pk_fma_f32 v[48:49], v[48:49], v[136:137], v[196:197]
	v_pk_fma_f32 v[50:51], v[50:51], v[138:139], v[198:199]
	v_cvt_pk_bf16_f32 v48, v48, v49
	v_cvt_pk_bf16_f32 v49, v50, v51
	global_store_dwordx2 v[170:171], v[48:49], off
	s_waitcnt vmcnt(25)
	v_pk_fma_f32 v[40:41], v[40:41], v[140:141], v[200:201]
	v_pk_fma_f32 v[42:43], v[42:43], v[142:143], v[202:203]
	v_cvt_pk_bf16_f32 v40, v40, v41
	v_cvt_pk_bf16_f32 v41, v42, v43
	global_store_dwordx2 v[170:171], v[40:41], off offset:32
	s_waitcnt vmcnt(24)
	v_pk_fma_f32 v[36:37], v[36:37], v[132:133], v[204:205]
	v_pk_fma_f32 v[38:39], v[38:39], v[134:135], v[206:207]
	v_cvt_pk_bf16_f32 v36, v36, v37
	v_cvt_pk_bf16_f32 v37, v38, v39
	global_store_dwordx2 v[170:171], v[36:37], off offset:256
	s_waitcnt vmcnt(23)
	v_pk_fma_f32 v[28:29], v[28:29], v[128:129], v[208:209]
	v_pk_fma_f32 v[30:31], v[30:31], v[130:131], v[210:211]
	v_cvt_pk_bf16_f32 v28, v28, v29
	v_cvt_pk_bf16_f32 v29, v30, v31
	global_store_dwordx2 v[170:171], v[28:29], off offset:288
	s_mov_b32 s28, 0xa0000
	v_lshl_add_u64 v[170:171], v[176:177], 0, s[28:29]
	s_waitcnt vmcnt(22)
	v_pk_fma_f32 v[32:33], v[32:33], v[136:137], v[212:213]
	v_pk_fma_f32 v[34:35], v[34:35], v[138:139], v[214:215]
	v_cvt_pk_bf16_f32 v32, v32, v33
	v_cvt_pk_bf16_f32 v33, v34, v35
	global_store_dwordx2 v[170:171], v[32:33], off
	s_waitcnt vmcnt(21)
	v_pk_fma_f32 v[24:25], v[24:25], v[140:141], v[216:217]
	v_pk_fma_f32 v[26:27], v[26:27], v[142:143], v[218:219]
	v_cvt_pk_bf16_f32 v24, v24, v25
	v_cvt_pk_bf16_f32 v25, v26, v27
	global_store_dwordx2 v[170:171], v[24:25], off offset:32
	s_waitcnt vmcnt(20)
	v_pk_fma_f32 v[20:21], v[20:21], v[132:133], v[220:221]
	v_pk_fma_f32 v[22:23], v[22:23], v[134:135], v[222:223]
	v_cvt_pk_bf16_f32 v20, v20, v21
	v_cvt_pk_bf16_f32 v21, v22, v23
	global_store_dwordx2 v[170:171], v[20:21], off offset:256
	s_waitcnt vmcnt(19)
	v_pk_fma_f32 v[12:13], v[12:13], v[128:129], v[224:225]
	v_pk_fma_f32 v[14:15], v[14:15], v[130:131], v[226:227]
	v_cvt_pk_bf16_f32 v12, v12, v13
	v_cvt_pk_bf16_f32 v13, v14, v15
	global_store_dwordx2 v[170:171], v[12:13], off offset:288
	s_mov_b32 s28, 0xb0000
	v_lshl_add_u64 v[170:171], v[176:177], 0, s[28:29]
	s_waitcnt vmcnt(18)
	v_pk_fma_f32 v[16:17], v[16:17], v[136:137], v[228:229]
	v_pk_fma_f32 v[18:19], v[18:19], v[138:139], v[230:231]
	v_cvt_pk_bf16_f32 v16, v16, v17
	v_cvt_pk_bf16_f32 v17, v18, v19
	global_store_dwordx2 v[170:171], v[16:17], off
	s_waitcnt vmcnt(17)
	v_pk_fma_f32 v[8:9], v[8:9], v[140:141], v[232:233]
	v_pk_fma_f32 v[10:11], v[10:11], v[142:143], v[234:235]
	v_cvt_pk_bf16_f32 v8, v8, v9
	v_cvt_pk_bf16_f32 v9, v10, v11
	global_store_dwordx2 v[170:171], v[8:9], off offset:32
	s_waitcnt vmcnt(16)
	v_pk_fma_f32 v[4:5], v[4:5], v[132:133], v[236:237]
	v_pk_fma_f32 v[6:7], v[6:7], v[134:135], v[238:239]
	v_cvt_pk_bf16_f32 v4, v4, v5
	v_cvt_pk_bf16_f32 v5, v6, v7
	global_store_dwordx2 v[170:171], v[4:5], off offset:256
	s_waitcnt vmcnt(15)
	v_pk_fma_f32 v[0:1], v[0:1], v[128:129], v[240:241]
	v_pk_fma_f32 v[2:3], v[2:3], v[130:131], v[242:243]
	v_cvt_pk_bf16_f32 v0, v0, v1
	v_cvt_pk_bf16_f32 v1, v2, v3
	global_store_dwordx2 v[170:171], v[0:1], off offset:288
	s_and_b64 vcc, exec, s[34:35]
	s_cbranch_vccz .LBB0_1065
	s_branch .LBB0_1077
